# residual epilogue loads and stores marked non-temporal (streaming) so they do not displace GEMM operands in L2
# speedup vs baseline: 1.0030x; 1.0030x over previous
;     ...
; #pragma unroll
;     for (int ai = 0; ai < 2; ++ai)
; #pragma unroll
;       for (int m = 0; m < 4; ++m)
;         epi(brow + ai * HALF + wr * 64 + m * 16 + fr, bcol + wc * 32, fq, acc[ai][0][m][0], acc[ai][0][m][1], acc[ai][1][m][0], acc[ai][1][m][1]);
.LBB0_1463:
	v_or_b32_e32 v0, s10, v218
	v_add_u32_e32 v136, v0, v215
	v_ashrrev_i32_e32 v137, 31, v136
	v_readlane_b32 s6, v253, 60
	v_lshl_or_b32 v0, v139, 5, s90
	v_lshlrev_b64 v[132:133], 12, v[136:137]
	v_readlane_b32 s7, v253, 61
	v_lshlrev_b64 v[134:135], 2, v[0:1]
	v_mov_b32_e32 v131, v1
	v_lshl_add_u64 v[132:133], s[6:7], 0, v[132:133]
	v_lshl_add_u64 v[132:133], v[132:133], 0, v[134:135]
	v_lshl_add_u64 v[132:133], v[132:133], 0, v[130:131]
	v_cndmask_b32_e64 v0, 0, 1, s[4:5]
	v_and_b32_e32 v134, 1, v210
	v_cmp_eq_u32_e32 vcc, 0, v134
	s_nop 1
	v_mov_b32_e32 v135, 0xfffff040
	v_cndmask_b32_e32 v134, v135, v1, vcc
	v_cndmask_b32_e32 v135, -1, v1, vcc
	v_lshl_add_u64 v[132:133], v[132:133], 0, v[134:135]
	s_mov_b64 s[6:7], 0x1000
	v_lshl_add_u64 v[136:137], v[132:133], 0, s[6:7]
	v_mov_b64_e32 v[138:139], v[132:133]
	v_mov_b64_e32 v[140:141], v[136:137]
	global_load_dwordx4 v[168:171], v[138:139], off nt
	global_load_dwordx4 v[172:175], v[140:141], off nt
	global_load_dwordx4 v[176:179], v[138:139], off offset:512 nt
	global_load_dwordx4 v[180:183], v[140:141], off offset:512 nt
	s_mov_b64 s[6:7], 0x10000
	v_lshl_add_u64 v[142:143], v[132:133], 0, s[6:7]
	v_lshl_add_u64 v[144:145], v[136:137], 0, s[6:7]
	global_load_dwordx4 v[184:187], v[142:143], off nt
	global_load_dwordx4 v[188:191], v[144:145], off nt
	global_load_dwordx4 v[192:195], v[142:143], off offset:512 nt
	global_load_dwordx4 v[196:199], v[144:145], off offset:512 nt
	s_mov_b64 s[6:7], 0x20000
	v_lshl_add_u64 v[146:147], v[132:133], 0, s[6:7]
	v_lshl_add_u64 v[148:149], v[136:137], 0, s[6:7]
	global_load_dwordx4 v[220:223], v[146:147], off nt
	global_load_dwordx4 v[224:227], v[148:149], off nt
	global_load_dwordx4 v[228:231], v[146:147], off offset:512 nt
	global_load_dwordx4 v[232:235], v[148:149], off offset:512 nt
	s_mov_b64 s[6:7], 0x30000
	v_lshl_add_u64 v[150:151], v[132:133], 0, s[6:7]
	v_lshl_add_u64 v[152:153], v[136:137], 0, s[6:7]
	global_load_dwordx4 v[236:239], v[150:151], off nt
	global_load_dwordx4 v[240:243], v[152:153], off nt
	global_load_dwordx4 v[244:247], v[150:151], off offset:512 nt
	global_load_dwordx4 v[248:251], v[152:153], off offset:512 nt
	v_mov_b32_dpp v200, v118 quad_perm:[1,0,3,2] row_mask:0xf bank_mask:0xf
	v_cndmask_b32_dpp v201, v114, v200, vcc quad_perm:[1,0,3,2] row_mask:0xf bank_mask:0xf
	v_cndmask_b32_e32 v118, v201, v118, vcc
	v_cndmask_b32_e32 v114, v114, v201, vcc
	v_mov_b32_dpp v200, v119 quad_perm:[1,0,3,2] row_mask:0xf bank_mask:0xf
	v_cndmask_b32_dpp v201, v115, v200, vcc quad_perm:[1,0,3,2] row_mask:0xf bank_mask:0xf
	v_cndmask_b32_e32 v119, v201, v119, vcc
	v_cndmask_b32_e32 v115, v115, v201, vcc
	v_mov_b32_dpp v200, v120 quad_perm:[1,0,3,2] row_mask:0xf bank_mask:0xf
	v_cndmask_b32_dpp v201, v116, v200, vcc quad_perm:[1,0,3,2] row_mask:0xf bank_mask:0xf
	v_cndmask_b32_e32 v120, v201, v120, vcc
	v_cndmask_b32_e32 v116, v116, v201, vcc
	v_mov_b32_dpp v200, v121 quad_perm:[1,0,3,2] row_mask:0xf bank_mask:0xf
	v_cndmask_b32_dpp v201, v117, v200, vcc quad_perm:[1,0,3,2] row_mask:0xf bank_mask:0xf
	v_cndmask_b32_e32 v121, v201, v121, vcc
	v_cndmask_b32_e32 v117, v117, v201, vcc
	v_mov_b32_dpp v200, v126 quad_perm:[1,0,3,2] row_mask:0xf bank_mask:0xf
	v_cndmask_b32_dpp v201, v122, v200, vcc quad_perm:[1,0,3,2] row_mask:0xf bank_mask:0xf
	v_cndmask_b32_e32 v126, v201, v126, vcc
	v_cndmask_b32_e32 v122, v122, v201, vcc
	v_mov_b32_dpp v200, v127 quad_perm:[1,0,3,2] row_mask:0xf bank_mask:0xf
	v_cndmask_b32_dpp v201, v123, v200, vcc quad_perm:[1,0,3,2] row_mask:0xf bank_mask:0xf
	v_cndmask_b32_e32 v127, v201, v127, vcc
	v_cndmask_b32_e32 v123, v123, v201, vcc
	v_mov_b32_dpp v200, v128 quad_perm:[1,0,3,2] row_mask:0xf bank_mask:0xf
	v_cndmask_b32_dpp v201, v124, v200, vcc quad_perm:[1,0,3,2] row_mask:0xf bank_mask:0xf
	v_cndmask_b32_e32 v128, v201, v128, vcc
	v_cndmask_b32_e32 v124, v124, v201, vcc
	v_mov_b32_dpp v200, v129 quad_perm:[1,0,3,2] row_mask:0xf bank_mask:0xf
	v_cndmask_b32_dpp v201, v125, v200, vcc quad_perm:[1,0,3,2] row_mask:0xf bank_mask:0xf
	v_cndmask_b32_e32 v129, v201, v129, vcc
	v_cndmask_b32_e32 v125, v125, v201, vcc
	s_waitcnt vmcnt(12)
	v_pk_add_f32 v[168:169], v[118:119], v[168:169]
	v_pk_add_f32 v[170:171], v[120:121], v[170:171]
	v_pk_add_f32 v[172:173], v[114:115], v[172:173]
	v_pk_add_f32 v[174:175], v[116:117], v[174:175]
	v_pk_add_f32 v[176:177], v[126:127], v[176:177]
	v_pk_add_f32 v[178:179], v[128:129], v[178:179]
	v_pk_add_f32 v[180:181], v[122:123], v[180:181]
	v_pk_add_f32 v[182:183], v[124:125], v[182:183]
	global_store_dwordx4 v[138:139], v[168:171], off sc1 nt
	global_store_dwordx4 v[140:141], v[172:175], off sc1 nt
	global_store_dwordx4 v[138:139], v[176:179], off offset:512 sc1 nt
	global_store_dwordx4 v[140:141], v[180:183], off offset:512 sc1 nt
	s_nop 1
	s_mov_b64 s[6:7], 0x80000
	v_lshl_add_u64 v[138:139], v[132:133], 0, s[6:7]
	v_lshl_add_u64 v[140:141], v[136:137], 0, s[6:7]
	global_load_dwordx4 v[168:171], v[138:139], off nt
	global_load_dwordx4 v[172:175], v[140:141], off nt
	global_load_dwordx4 v[176:179], v[138:139], off offset:512 nt
	global_load_dwordx4 v[180:183], v[140:141], off offset:512 nt
	v_mov_b32_dpp v200, v102 quad_perm:[1,0,3,2] row_mask:0xf bank_mask:0xf
	v_cndmask_b32_dpp v201, v98, v200, vcc quad_perm:[1,0,3,2] row_mask:0xf bank_mask:0xf
	v_cndmask_b32_e32 v102, v201, v102, vcc
	v_cndmask_b32_e32 v98, v98, v201, vcc
	v_mov_b32_dpp v200, v103 quad_perm:[1,0,3,2] row_mask:0xf bank_mask:0xf
	v_cndmask_b32_dpp v201, v99, v200, vcc quad_perm:[1,0,3,2] row_mask:0xf bank_mask:0xf
	v_cndmask_b32_e32 v103, v201, v103, vcc
	v_cndmask_b32_e32 v99, v99, v201, vcc
;     ...
; #pragma unroll
;     for (int ai = 0; ai < 2; ++ai)
; #pragma unroll
;       for (int m = 0; m < 4; ++m)
;         epi(brow + ai * HALF + wr * 64 + m * 16 + fr, bcol + wc * 32, fq, acc[ai][0][m][0], acc[ai][0][m][1], acc[ai][1][m][0], acc[ai][1][m][1]);
	v_mov_b32_dpp v200, v104 quad_perm:[1,0,3,2] row_mask:0xf bank_mask:0xf
	v_cndmask_b32_dpp v201, v100, v200, vcc quad_perm:[1,0,3,2] row_mask:0xf bank_mask:0xf
	v_cndmask_b32_e32 v104, v201, v104, vcc
	v_cndmask_b32_e32 v100, v100, v201, vcc
	v_mov_b32_dpp v200, v105 quad_perm:[1,0,3,2] row_mask:0xf bank_mask:0xf
	v_cndmask_b32_dpp v201, v101, v200, vcc quad_perm:[1,0,3,2] row_mask:0xf bank_mask:0xf
	v_cndmask_b32_e32 v105, v201, v105, vcc
	v_cndmask_b32_e32 v101, v101, v201, vcc
	v_mov_b32_dpp v200, v110 quad_perm:[1,0,3,2] row_mask:0xf bank_mask:0xf
	v_cndmask_b32_dpp v201, v106, v200, vcc quad_perm:[1,0,3,2] row_mask:0xf bank_mask:0xf
	v_cndmask_b32_e32 v110, v201, v110, vcc
	v_cndmask_b32_e32 v106, v106, v201, vcc
	v_mov_b32_dpp v200, v111 quad_perm:[1,0,3,2] row_mask:0xf bank_mask:0xf
	v_cndmask_b32_dpp v201, v107, v200, vcc quad_perm:[1,0,3,2] row_mask:0xf bank_mask:0xf
	v_cndmask_b32_e32 v111, v201, v111, vcc
	v_cndmask_b32_e32 v107, v107, v201, vcc
	v_mov_b32_dpp v200, v112 quad_perm:[1,0,3,2] row_mask:0xf bank_mask:0xf
	v_cndmask_b32_dpp v201, v108, v200, vcc quad_perm:[1,0,3,2] row_mask:0xf bank_mask:0xf
	v_cndmask_b32_e32 v112, v201, v112, vcc
	v_cndmask_b32_e32 v108, v108, v201, vcc
	v_mov_b32_dpp v200, v113 quad_perm:[1,0,3,2] row_mask:0xf bank_mask:0xf
	v_cndmask_b32_dpp v201, v109, v200, vcc quad_perm:[1,0,3,2] row_mask:0xf bank_mask:0xf
	v_cndmask_b32_e32 v113, v201, v113, vcc
	v_cndmask_b32_e32 v109, v109, v201, vcc
	s_waitcnt vmcnt(16)
	v_pk_add_f32 v[184:185], v[102:103], v[184:185]
	v_pk_add_f32 v[186:187], v[104:105], v[186:187]
	v_pk_add_f32 v[188:189], v[98:99], v[188:189]
	v_pk_add_f32 v[190:191], v[100:101], v[190:191]
	v_pk_add_f32 v[192:193], v[110:111], v[192:193]
	v_pk_add_f32 v[194:195], v[112:113], v[194:195]
	v_pk_add_f32 v[196:197], v[106:107], v[196:197]
	v_pk_add_f32 v[198:199], v[108:109], v[198:199]
	global_store_dwordx4 v[142:143], v[184:187], off sc1 nt
	global_store_dwordx4 v[144:145], v[188:191], off sc1 nt
	global_store_dwordx4 v[142:143], v[192:195], off offset:512 sc1 nt
	global_store_dwordx4 v[144:145], v[196:199], off offset:512 sc1 nt
	s_nop 1
	s_mov_b64 s[6:7], 0x90000
	v_lshl_add_u64 v[142:143], v[132:133], 0, s[6:7]
	v_lshl_add_u64 v[144:145], v[136:137], 0, s[6:7]
	global_load_dwordx4 v[184:187], v[142:143], off nt
	global_load_dwordx4 v[188:191], v[144:145], off nt
	global_load_dwordx4 v[192:195], v[142:143], off offset:512 nt
	global_load_dwordx4 v[196:199], v[144:145], off offset:512 nt
	v_mov_b32_dpp v200, v86 quad_perm:[1,0,3,2] row_mask:0xf bank_mask:0xf
	v_cndmask_b32_dpp v201, v82, v200, vcc quad_perm:[1,0,3,2] row_mask:0xf bank_mask:0xf
	v_cndmask_b32_e32 v86, v201, v86, vcc
	v_cndmask_b32_e32 v82, v82, v201, vcc
	v_mov_b32_dpp v200, v87 quad_perm:[1,0,3,2] row_mask:0xf bank_mask:0xf
	v_cndmask_b32_dpp v201, v83, v200, vcc quad_perm:[1,0,3,2] row_mask:0xf bank_mask:0xf
	v_cndmask_b32_e32 v87, v201, v87, vcc
	v_cndmask_b32_e32 v83, v83, v201, vcc
	v_mov_b32_dpp v200, v88 quad_perm:[1,0,3,2] row_mask:0xf bank_mask:0xf
	v_cndmask_b32_dpp v201, v84, v200, vcc quad_perm:[1,0,3,2] row_mask:0xf bank_mask:0xf
	v_cndmask_b32_e32 v88, v201, v88, vcc
	v_cndmask_b32_e32 v84, v84, v201, vcc
	v_mov_b32_dpp v200, v89 quad_perm:[1,0,3,2] row_mask:0xf bank_mask:0xf
	v_cndmask_b32_dpp v201, v85, v200, vcc quad_perm:[1,0,3,2] row_mask:0xf bank_mask:0xf
	v_cndmask_b32_e32 v89, v201, v89, vcc
	v_cndmask_b32_e32 v85, v85, v201, vcc
	v_mov_b32_dpp v200, v94 quad_perm:[1,0,3,2] row_mask:0xf bank_mask:0xf
	v_cndmask_b32_dpp v201, v90, v200, vcc quad_perm:[1,0,3,2] row_mask:0xf bank_mask:0xf
	v_cndmask_b32_e32 v94, v201, v94, vcc
	v_cndmask_b32_e32 v90, v90, v201, vcc
	v_mov_b32_dpp v200, v95 quad_perm:[1,0,3,2] row_mask:0xf bank_mask:0xf
	v_cndmask_b32_dpp v201, v91, v200, vcc quad_perm:[1,0,3,2] row_mask:0xf bank_mask:0xf
	v_cndmask_b32_e32 v95, v201, v95, vcc
	v_cndmask_b32_e32 v91, v91, v201, vcc
	v_mov_b32_dpp v200, v96 quad_perm:[1,0,3,2] row_mask:0xf bank_mask:0xf
	v_cndmask_b32_dpp v201, v92, v200, vcc quad_perm:[1,0,3,2] row_mask:0xf bank_mask:0xf
	v_cndmask_b32_e32 v96, v201, v96, vcc
	v_cndmask_b32_e32 v92, v92, v201, vcc
	v_mov_b32_dpp v200, v97 quad_perm:[1,0,3,2] row_mask:0xf bank_mask:0xf
	v_cndmask_b32_dpp v201, v93, v200, vcc quad_perm:[1,0,3,2] row_mask:0xf bank_mask:0xf
	v_cndmask_b32_e32 v97, v201, v97, vcc
	v_cndmask_b32_e32 v93, v93, v201, vcc
	s_waitcnt vmcnt(20)
;     ...
; #pragma unroll
;     for (int ai = 0; ai < 2; ++ai)
; #pragma unroll
;       for (int m = 0; m < 4; ++m)
;         epi(brow + ai * HALF + wr * 64 + m * 16 + fr, bcol + wc * 32, fq, acc[ai][0][m][0], acc[ai][0][m][1], acc[ai][1][m][0], acc[ai][1][m][1]);
	v_pk_add_f32 v[220:221], v[86:87], v[220:221]
	v_pk_add_f32 v[222:223], v[88:89], v[222:223]
	v_pk_add_f32 v[224:225], v[82:83], v[224:225]
	v_pk_add_f32 v[226:227], v[84:85], v[226:227]
	v_pk_add_f32 v[228:229], v[94:95], v[228:229]
	v_pk_add_f32 v[230:231], v[96:97], v[230:231]
	v_pk_add_f32 v[232:233], v[90:91], v[232:233]
	v_pk_add_f32 v[234:235], v[92:93], v[234:235]
	global_store_dwordx4 v[146:147], v[220:223], off sc1 nt
	global_store_dwordx4 v[148:149], v[224:227], off sc1 nt
	global_store_dwordx4 v[146:147], v[228:231], off offset:512 sc1 nt
	global_store_dwordx4 v[148:149], v[232:235], off offset:512 sc1 nt
	s_nop 1
	s_mov_b64 s[6:7], 0xa0000
	v_lshl_add_u64 v[146:147], v[132:133], 0, s[6:7]
	v_lshl_add_u64 v[148:149], v[136:137], 0, s[6:7]
	global_load_dwordx4 v[220:223], v[146:147], off nt
	global_load_dwordx4 v[224:227], v[148:149], off nt
	global_load_dwordx4 v[228:231], v[146:147], off offset:512 nt
	global_load_dwordx4 v[232:235], v[148:149], off offset:512 nt
	v_mov_b32_dpp v200, v70 quad_perm:[1,0,3,2] row_mask:0xf bank_mask:0xf
	v_cndmask_b32_dpp v201, v66, v200, vcc quad_perm:[1,0,3,2] row_mask:0xf bank_mask:0xf
	v_cndmask_b32_e32 v70, v201, v70, vcc
	v_cndmask_b32_e32 v66, v66, v201, vcc
	v_mov_b32_dpp v200, v71 quad_perm:[1,0,3,2] row_mask:0xf bank_mask:0xf
	v_cndmask_b32_dpp v201, v67, v200, vcc quad_perm:[1,0,3,2] row_mask:0xf bank_mask:0xf
	v_cndmask_b32_e32 v71, v201, v71, vcc
	v_cndmask_b32_e32 v67, v67, v201, vcc
	v_mov_b32_dpp v200, v72 quad_perm:[1,0,3,2] row_mask:0xf bank_mask:0xf
	v_cndmask_b32_dpp v201, v68, v200, vcc quad_perm:[1,0,3,2] row_mask:0xf bank_mask:0xf
	v_cndmask_b32_e32 v72, v201, v72, vcc
	v_cndmask_b32_e32 v68, v68, v201, vcc
	v_mov_b32_dpp v200, v73 quad_perm:[1,0,3,2] row_mask:0xf bank_mask:0xf
	v_cndmask_b32_dpp v201, v69, v200, vcc quad_perm:[1,0,3,2] row_mask:0xf bank_mask:0xf
	v_cndmask_b32_e32 v73, v201, v73, vcc
	v_cndmask_b32_e32 v69, v69, v201, vcc
	v_mov_b32_dpp v200, v78 quad_perm:[1,0,3,2] row_mask:0xf bank_mask:0xf
	v_cndmask_b32_dpp v201, v74, v200, vcc quad_perm:[1,0,3,2] row_mask:0xf bank_mask:0xf
	v_cndmask_b32_e32 v78, v201, v78, vcc
	v_cndmask_b32_e32 v74, v74, v201, vcc
	v_mov_b32_dpp v200, v79 quad_perm:[1,0,3,2] row_mask:0xf bank_mask:0xf
	v_cndmask_b32_dpp v201, v75, v200, vcc quad_perm:[1,0,3,2] row_mask:0xf bank_mask:0xf
	v_cndmask_b32_e32 v79, v201, v79, vcc
	v_cndmask_b32_e32 v75, v75, v201, vcc
	v_mov_b32_dpp v200, v80 quad_perm:[1,0,3,2] row_mask:0xf bank_mask:0xf
	v_cndmask_b32_dpp v201, v76, v200, vcc quad_perm:[1,0,3,2] row_mask:0xf bank_mask:0xf
	v_cndmask_b32_e32 v80, v201, v80, vcc
	v_cndmask_b32_e32 v76, v76, v201, vcc
	v_mov_b32_dpp v200, v81 quad_perm:[1,0,3,2] row_mask:0xf bank_mask:0xf
	v_cndmask_b32_dpp v201, v77, v200, vcc quad_perm:[1,0,3,2] row_mask:0xf bank_mask:0xf
	v_cndmask_b32_e32 v81, v201, v81, vcc
	v_cndmask_b32_e32 v77, v77, v201, vcc
	s_waitcnt vmcnt(24)
	v_pk_add_f32 v[236:237], v[70:71], v[236:237]
	v_pk_add_f32 v[238:239], v[72:73], v[238:239]
	v_pk_add_f32 v[240:241], v[66:67], v[240:241]
	v_pk_add_f32 v[242:243], v[68:69], v[242:243]
	v_pk_add_f32 v[244:245], v[78:79], v[244:245]
	v_pk_add_f32 v[246:247], v[80:81], v[246:247]
	v_pk_add_f32 v[248:249], v[74:75], v[248:249]
	v_pk_add_f32 v[250:251], v[76:77], v[250:251]
	global_store_dwordx4 v[150:151], v[236:239], off sc1 nt
	global_store_dwordx4 v[152:153], v[240:243], off sc1 nt
	global_store_dwordx4 v[150:151], v[244:247], off offset:512 sc1 nt
	global_store_dwordx4 v[152:153], v[248:251], off offset:512 sc1 nt
	s_nop 1
	s_mov_b64 s[6:7], 0xb0000
	v_lshl_add_u64 v[150:151], v[132:133], 0, s[6:7]
	v_lshl_add_u64 v[152:153], v[136:137], 0, s[6:7]
	global_load_dwordx4 v[236:239], v[150:151], off nt
	global_load_dwordx4 v[240:243], v[152:153], off nt
	global_load_dwordx4 v[244:247], v[150:151], off offset:512 nt
	global_load_dwordx4 v[248:251], v[152:153], off offset:512 nt
	v_mov_b32_dpp v200, v54 quad_perm:[1,0,3,2] row_mask:0xf bank_mask:0xf
	v_cndmask_b32_dpp v201, v50, v200, vcc quad_perm:[1,0,3,2] row_mask:0xf bank_mask:0xf
	v_cndmask_b32_e32 v54, v201, v54, vcc
	v_cndmask_b32_e32 v50, v50, v201, vcc
	v_mov_b32_dpp v200, v55 quad_perm:[1,0,3,2] row_mask:0xf bank_mask:0xf
	v_cndmask_b32_dpp v201, v51, v200, vcc quad_perm:[1,0,3,2] row_mask:0xf bank_mask:0xf
	v_cndmask_b32_e32 v55, v201, v55, vcc
	v_cndmask_b32_e32 v51, v51, v201, vcc
	v_mov_b32_dpp v200, v56 quad_perm:[1,0,3,2] row_mask:0xf bank_mask:0xf
	v_cndmask_b32_dpp v201, v52, v200, vcc quad_perm:[1,0,3,2] row_mask:0xf bank_mask:0xf
	v_cndmask_b32_e32 v56, v201, v56, vcc
	v_cndmask_b32_e32 v52, v52, v201, vcc
	v_mov_b32_dpp v200, v57 quad_perm:[1,0,3,2] row_mask:0xf bank_mask:0xf
	v_cndmask_b32_dpp v201, v53, v200, vcc quad_perm:[1,0,3,2] row_mask:0xf bank_mask:0xf
	v_cndmask_b32_e32 v57, v201, v57, vcc
	v_cndmask_b32_e32 v53, v53, v201, vcc
	v_mov_b32_dpp v200, v62 quad_perm:[1,0,3,2] row_mask:0xf bank_mask:0xf
	v_cndmask_b32_dpp v201, v58, v200, vcc quad_perm:[1,0,3,2] row_mask:0xf bank_mask:0xf
	v_cndmask_b32_e32 v62, v201, v62, vcc
	v_cndmask_b32_e32 v58, v58, v201, vcc
	v_mov_b32_dpp v200, v63 quad_perm:[1,0,3,2] row_mask:0xf bank_mask:0xf
	v_cndmask_b32_dpp v201, v59, v200, vcc quad_perm:[1,0,3,2] row_mask:0xf bank_mask:0xf
	v_cndmask_b32_e32 v63, v201, v63, vcc
	v_cndmask_b32_e32 v59, v59, v201, vcc
	v_mov_b32_dpp v200, v64 quad_perm:[1,0,3,2] row_mask:0xf bank_mask:0xf
	v_cndmask_b32_dpp v201, v60, v200, vcc quad_perm:[1,0,3,2] row_mask:0xf bank_mask:0xf
	v_cndmask_b32_e32 v64, v201, v64, vcc
	v_cndmask_b32_e32 v60, v60, v201, vcc
	v_mov_b32_dpp v200, v65 quad_perm:[1,0,3,2] row_mask:0xf bank_mask:0xf
	v_cndmask_b32_dpp v201, v61, v200, vcc quad_perm:[1,0,3,2] row_mask:0xf bank_mask:0xf
	v_cndmask_b32_e32 v65, v201, v65, vcc
	v_cndmask_b32_e32 v61, v61, v201, vcc
	s_waitcnt vmcnt(24)
;     ...
; #pragma unroll
;     for (int ai = 0; ai < 2; ++ai)
; #pragma unroll
;       for (int m = 0; m < 4; ++m)
;         epi(brow + ai * HALF + wr * 64 + m * 16 + fr, bcol + wc * 32, fq, acc[ai][0][m][0], acc[ai][0][m][1], acc[ai][1][m][0], acc[ai][1][m][1]);
	v_pk_add_f32 v[168:169], v[54:55], v[168:169]
	v_pk_add_f32 v[170:171], v[56:57], v[170:171]
	v_pk_add_f32 v[172:173], v[50:51], v[172:173]
	v_pk_add_f32 v[174:175], v[52:53], v[174:175]
	v_pk_add_f32 v[176:177], v[62:63], v[176:177]
	v_pk_add_f32 v[178:179], v[64:65], v[178:179]
	v_pk_add_f32 v[180:181], v[58:59], v[180:181]
	v_pk_add_f32 v[182:183], v[60:61], v[182:183]
	global_store_dwordx4 v[138:139], v[168:171], off sc1 nt
	global_store_dwordx4 v[140:141], v[172:175], off sc1 nt
	global_store_dwordx4 v[138:139], v[176:179], off offset:512 sc1 nt
	global_store_dwordx4 v[140:141], v[180:183], off offset:512 sc1 nt
	v_mov_b32_dpp v200, v38 quad_perm:[1,0,3,2] row_mask:0xf bank_mask:0xf
	v_cndmask_b32_dpp v201, v34, v200, vcc quad_perm:[1,0,3,2] row_mask:0xf bank_mask:0xf
	v_cndmask_b32_e32 v38, v201, v38, vcc
	v_cndmask_b32_e32 v34, v34, v201, vcc
	v_mov_b32_dpp v200, v39 quad_perm:[1,0,3,2] row_mask:0xf bank_mask:0xf
	v_cndmask_b32_dpp v201, v35, v200, vcc quad_perm:[1,0,3,2] row_mask:0xf bank_mask:0xf
	v_cndmask_b32_e32 v39, v201, v39, vcc
	v_cndmask_b32_e32 v35, v35, v201, vcc
	v_mov_b32_dpp v200, v40 quad_perm:[1,0,3,2] row_mask:0xf bank_mask:0xf
	v_cndmask_b32_dpp v201, v36, v200, vcc quad_perm:[1,0,3,2] row_mask:0xf bank_mask:0xf
	v_cndmask_b32_e32 v40, v201, v40, vcc
	v_cndmask_b32_e32 v36, v36, v201, vcc
	v_mov_b32_dpp v200, v41 quad_perm:[1,0,3,2] row_mask:0xf bank_mask:0xf
	v_cndmask_b32_dpp v201, v37, v200, vcc quad_perm:[1,0,3,2] row_mask:0xf bank_mask:0xf
	v_cndmask_b32_e32 v41, v201, v41, vcc
	v_cndmask_b32_e32 v37, v37, v201, vcc
	v_mov_b32_dpp v200, v46 quad_perm:[1,0,3,2] row_mask:0xf bank_mask:0xf
	v_cndmask_b32_dpp v201, v42, v200, vcc quad_perm:[1,0,3,2] row_mask:0xf bank_mask:0xf
	v_cndmask_b32_e32 v46, v201, v46, vcc
	v_cndmask_b32_e32 v42, v42, v201, vcc
	v_mov_b32_dpp v200, v47 quad_perm:[1,0,3,2] row_mask:0xf bank_mask:0xf
	v_cndmask_b32_dpp v201, v43, v200, vcc quad_perm:[1,0,3,2] row_mask:0xf bank_mask:0xf
	v_cndmask_b32_e32 v47, v201, v47, vcc
	v_cndmask_b32_e32 v43, v43, v201, vcc
	v_mov_b32_dpp v200, v48 quad_perm:[1,0,3,2] row_mask:0xf bank_mask:0xf
	v_cndmask_b32_dpp v201, v44, v200, vcc quad_perm:[1,0,3,2] row_mask:0xf bank_mask:0xf
	v_cndmask_b32_e32 v48, v201, v48, vcc
	v_cndmask_b32_e32 v44, v44, v201, vcc
	v_mov_b32_dpp v200, v49 quad_perm:[1,0,3,2] row_mask:0xf bank_mask:0xf
	v_cndmask_b32_dpp v201, v45, v200, vcc quad_perm:[1,0,3,2] row_mask:0xf bank_mask:0xf
	v_cndmask_b32_e32 v49, v201, v49, vcc
	v_cndmask_b32_e32 v45, v45, v201, vcc
	s_waitcnt vmcnt(20)
	v_pk_add_f32 v[184:185], v[38:39], v[184:185]
	v_pk_add_f32 v[186:187], v[40:41], v[186:187]
	v_pk_add_f32 v[188:189], v[34:35], v[188:189]
	v_pk_add_f32 v[190:191], v[36:37], v[190:191]
	v_pk_add_f32 v[192:193], v[46:47], v[192:193]
	v_pk_add_f32 v[194:195], v[48:49], v[194:195]
	v_pk_add_f32 v[196:197], v[42:43], v[196:197]
	v_pk_add_f32 v[198:199], v[44:45], v[198:199]
	global_store_dwordx4 v[142:143], v[184:187], off sc1 nt
	global_store_dwordx4 v[144:145], v[188:191], off sc1 nt
	global_store_dwordx4 v[142:143], v[192:195], off offset:512 sc1 nt
	global_store_dwordx4 v[144:145], v[196:199], off offset:512 sc1 nt
	v_mov_b32_dpp v200, v22 quad_perm:[1,0,3,2] row_mask:0xf bank_mask:0xf
	v_cndmask_b32_dpp v201, v18, v200, vcc quad_perm:[1,0,3,2] row_mask:0xf bank_mask:0xf
	v_cndmask_b32_e32 v22, v201, v22, vcc
	v_cndmask_b32_e32 v18, v18, v201, vcc
	v_mov_b32_dpp v200, v23 quad_perm:[1,0,3,2] row_mask:0xf bank_mask:0xf
	v_cndmask_b32_dpp v201, v19, v200, vcc quad_perm:[1,0,3,2] row_mask:0xf bank_mask:0xf
	v_cndmask_b32_e32 v23, v201, v23, vcc
	v_cndmask_b32_e32 v19, v19, v201, vcc
	v_mov_b32_dpp v200, v24 quad_perm:[1,0,3,2] row_mask:0xf bank_mask:0xf
	v_cndmask_b32_dpp v201, v20, v200, vcc quad_perm:[1,0,3,2] row_mask:0xf bank_mask:0xf
	v_cndmask_b32_e32 v24, v201, v24, vcc
	v_cndmask_b32_e32 v20, v20, v201, vcc
	v_mov_b32_dpp v200, v25 quad_perm:[1,0,3,2] row_mask:0xf bank_mask:0xf
	v_cndmask_b32_dpp v201, v21, v200, vcc quad_perm:[1,0,3,2] row_mask:0xf bank_mask:0xf
	v_cndmask_b32_e32 v25, v201, v25, vcc
	v_cndmask_b32_e32 v21, v21, v201, vcc
	v_mov_b32_dpp v200, v30 quad_perm:[1,0,3,2] row_mask:0xf bank_mask:0xf
	v_cndmask_b32_dpp v201, v26, v200, vcc quad_perm:[1,0,3,2] row_mask:0xf bank_mask:0xf
	v_cndmask_b32_e32 v30, v201, v30, vcc
	v_cndmask_b32_e32 v26, v26, v201, vcc
	v_mov_b32_dpp v200, v31 quad_perm:[1,0,3,2] row_mask:0xf bank_mask:0xf
	v_cndmask_b32_dpp v201, v27, v200, vcc quad_perm:[1,0,3,2] row_mask:0xf bank_mask:0xf
	v_cndmask_b32_e32 v31, v201, v31, vcc
	v_cndmask_b32_e32 v27, v27, v201, vcc
	v_mov_b32_dpp v200, v32 quad_perm:[1,0,3,2] row_mask:0xf bank_mask:0xf
	v_cndmask_b32_dpp v201, v28, v200, vcc quad_perm:[1,0,3,2] row_mask:0xf bank_mask:0xf
	v_cndmask_b32_e32 v32, v201, v32, vcc
	v_cndmask_b32_e32 v28, v28, v201, vcc
	v_mov_b32_dpp v200, v33 quad_perm:[1,0,3,2] row_mask:0xf bank_mask:0xf
	v_cndmask_b32_dpp v201, v29, v200, vcc quad_perm:[1,0,3,2] row_mask:0xf bank_mask:0xf
	v_cndmask_b32_e32 v33, v201, v33, vcc
	v_cndmask_b32_e32 v29, v29, v201, vcc
	s_waitcnt vmcnt(16)
; #define WAIT_V(n) asm volatile("s_waitcnt vmcnt(" #n ")" ::: "memory")
;     ...
; #pragma unroll
;     for (int ai = 0; ai < 2; ++ai)
; #pragma unroll
;       for (int m = 0; m < 4; ++m)
;         epi(brow + ai * HALF + wr * 64 + m * 16 + fr, bcol + wc * 32, fq, acc[ai][0][m][0], acc[ai][0][m][1], acc[ai][1][m][0], acc[ai][1][m][1]);
;   }
;   if (!have_next) { WAIT_V(0); __syncthreads(); }
	v_pk_add_f32 v[220:221], v[22:23], v[220:221]
	v_pk_add_f32 v[222:223], v[24:25], v[222:223]
	v_pk_add_f32 v[224:225], v[18:19], v[224:225]
	v_pk_add_f32 v[226:227], v[20:21], v[226:227]
	v_pk_add_f32 v[228:229], v[30:31], v[228:229]
	v_pk_add_f32 v[230:231], v[32:33], v[230:231]
	v_pk_add_f32 v[232:233], v[26:27], v[232:233]
	v_pk_add_f32 v[234:235], v[28:29], v[234:235]
	global_store_dwordx4 v[146:147], v[220:223], off sc1 nt
	global_store_dwordx4 v[148:149], v[224:227], off sc1 nt
	global_store_dwordx4 v[146:147], v[228:231], off offset:512 sc1 nt
	global_store_dwordx4 v[148:149], v[232:235], off offset:512 sc1 nt
	v_mov_b32_dpp v200, v14 quad_perm:[1,0,3,2] row_mask:0xf bank_mask:0xf
	v_cndmask_b32_dpp v201, v6, v200, vcc quad_perm:[1,0,3,2] row_mask:0xf bank_mask:0xf
	v_cndmask_b32_e32 v14, v201, v14, vcc
	v_cndmask_b32_e32 v6, v6, v201, vcc
	v_mov_b32_dpp v200, v15 quad_perm:[1,0,3,2] row_mask:0xf bank_mask:0xf
	v_cndmask_b32_dpp v201, v7, v200, vcc quad_perm:[1,0,3,2] row_mask:0xf bank_mask:0xf
	v_cndmask_b32_e32 v15, v201, v15, vcc
	v_cndmask_b32_e32 v7, v7, v201, vcc
	v_mov_b32_dpp v200, v16 quad_perm:[1,0,3,2] row_mask:0xf bank_mask:0xf
	v_cndmask_b32_dpp v201, v8, v200, vcc quad_perm:[1,0,3,2] row_mask:0xf bank_mask:0xf
	v_cndmask_b32_e32 v16, v201, v16, vcc
	v_cndmask_b32_e32 v8, v8, v201, vcc
	v_mov_b32_dpp v200, v17 quad_perm:[1,0,3,2] row_mask:0xf bank_mask:0xf
	v_cndmask_b32_dpp v201, v9, v200, vcc quad_perm:[1,0,3,2] row_mask:0xf bank_mask:0xf
	v_cndmask_b32_e32 v17, v201, v17, vcc
	v_cndmask_b32_e32 v9, v9, v201, vcc
	v_mov_b32_dpp v200, v10 quad_perm:[1,0,3,2] row_mask:0xf bank_mask:0xf
	v_cndmask_b32_dpp v201, v2, v200, vcc quad_perm:[1,0,3,2] row_mask:0xf bank_mask:0xf
	v_cndmask_b32_e32 v10, v201, v10, vcc
	v_cndmask_b32_e32 v2, v2, v201, vcc
	v_mov_b32_dpp v200, v11 quad_perm:[1,0,3,2] row_mask:0xf bank_mask:0xf
	v_cndmask_b32_dpp v201, v3, v200, vcc quad_perm:[1,0,3,2] row_mask:0xf bank_mask:0xf
	v_cndmask_b32_e32 v11, v201, v11, vcc
	v_cndmask_b32_e32 v3, v3, v201, vcc
	v_mov_b32_dpp v200, v12 quad_perm:[1,0,3,2] row_mask:0xf bank_mask:0xf
	v_cndmask_b32_dpp v201, v4, v200, vcc quad_perm:[1,0,3,2] row_mask:0xf bank_mask:0xf
	v_cndmask_b32_e32 v12, v201, v12, vcc
	v_cndmask_b32_e32 v4, v4, v201, vcc
	v_mov_b32_dpp v200, v13 quad_perm:[1,0,3,2] row_mask:0xf bank_mask:0xf
	v_cndmask_b32_dpp v201, v5, v200, vcc quad_perm:[1,0,3,2] row_mask:0xf bank_mask:0xf
	v_cndmask_b32_e32 v13, v201, v13, vcc
	v_cndmask_b32_e32 v5, v5, v201, vcc
	s_waitcnt vmcnt(12)
	v_pk_add_f32 v[236:237], v[14:15], v[236:237]
	v_pk_add_f32 v[238:239], v[16:17], v[238:239]
	v_pk_add_f32 v[240:241], v[6:7], v[240:241]
	v_pk_add_f32 v[242:243], v[8:9], v[242:243]
	v_pk_add_f32 v[244:245], v[10:11], v[244:245]
	v_pk_add_f32 v[246:247], v[12:13], v[246:247]
	v_pk_add_f32 v[248:249], v[2:3], v[248:249]
	v_pk_add_f32 v[250:251], v[4:5], v[250:251]
	global_store_dwordx4 v[150:151], v[236:239], off sc1 nt
	global_store_dwordx4 v[152:153], v[240:243], off sc1 nt
	global_store_dwordx4 v[150:151], v[244:247], off offset:512 sc1 nt
	global_store_dwordx4 v[152:153], v[248:251], off offset:512 sc1 nt
	v_cmp_ne_u32_e64 s[6:7], 1, v0
	s_andn2_b64 vcc, exec, s[4:5]
	s_cbranch_vccnz .LBB0_1450
	s_waitcnt vmcnt(0)
	s_waitcnt lgkmcnt(0)
	s_barrier
	s_branch .LBB0_1450

;     ...
; #pragma unroll
;     for (int ai = 0; ai < 2; ++ai)
; #pragma unroll
;       for (int m = 0; m < 4; ++m)
;         epi(brow + ai * HALF + wr * 64 + m * 16 + fr, bcol + wc * 32, fq, acc[ai][0][m][0], acc[ai][0][m][1], acc[ai][1][m][0], acc[ai][1][m][1]);
.LBB0_1487:
	v_or_b32_e32 v0, s8, v140
	v_readlane_b32 s16, v253, 24
	v_add_u32_e32 v136, v0, v141
	v_readlane_b32 s17, v253, 25
	v_ashrrev_i32_e32 v137, 31, v136
	v_readlane_b32 s18, v253, 26
	v_readlane_b32 s19, v253, 27
	v_readlane_b32 s20, v253, 28
	v_readlane_b32 s21, v253, 29
	s_mov_b64 s[8:9], s[16:17]
	v_lshl_or_b32 v0, v139, 5, s90
	s_mov_b32 s6, 0x8000
	v_lshlrev_b64 v[138:139], 12, v[136:137]
	s_mov_b64 s[10:11], s[18:19]
	v_lshlrev_b32_e32 v20, 12, v140
	v_mov_b32_e32 v21, v1
	v_cmp_gt_i32_e32 vcc, s6, v136
	v_lshl_add_u64 v[18:19], s[8:9], 0, v[138:139]
	v_lshl_add_u64 v[134:135], s[10:11], 0, v[20:21]
	v_readlane_b32 s10, v253, 60
	v_cndmask_b32_e32 v19, v135, v19, vcc
	v_cndmask_b32_e32 v18, v134, v18, vcc
	v_readlane_b32 s11, v253, 61
	v_lshlrev_b64 v[132:133], 2, v[0:1]
	v_mov_b32_e32 v131, v1
	v_lshl_add_u64 v[20:21], s[10:11], 0, v[138:139]
	v_lshl_add_u64 v[18:19], v[18:19], 0, v[132:133]
	v_lshl_add_u64 v[20:21], v[20:21], 0, v[132:133]
	v_lshl_add_u64 v[148:149], v[18:19], 0, v[130:131]
	v_lshl_add_u64 v[152:153], v[20:21], 0, v[130:131]
	v_readlane_b32 s22, v253, 30
	v_readlane_b32 s23, v253, 31
	v_readlane_b32 s24, v253, 32
	v_readlane_b32 s25, v253, 33
	v_readlane_b32 s26, v253, 34
	v_readlane_b32 s27, v253, 35
	v_readlane_b32 s28, v253, 36
	v_readlane_b32 s29, v253, 37
	v_readlane_b32 s30, v253, 38
	v_readlane_b32 s31, v253, 39
	s_mov_b64 s[12:13], s[20:21]
	v_sub_co_u32_e32 v134, vcc, v152, v148
	v_subb_co_u32_e32 v135, vcc, v153, v149, vcc
	s_nop 0
	v_readfirstlane_b32 s98, v134
	v_readfirstlane_b32 s99, v135
	v_and_b32_e32 v134, 1, v210
	v_cmp_eq_u32_e32 vcc, 0, v134
	s_nop 1
	v_mov_b32_e32 v135, 0xfffff040
	v_cndmask_b32_e32 v134, v135, v1, vcc
	v_cndmask_b32_e32 v135, -1, v1, vcc
	v_lshl_add_u64 v[132:133], v[148:149], 0, v[134:135]
	s_mov_b64 s[96:97], 0x1000
	v_lshl_add_u64 v[136:137], v[132:133], 0, s[96:97]
	v_mov_b64_e32 v[138:139], v[132:133]
	v_mov_b64_e32 v[140:141], v[136:137]
	global_load_dwordx4 v[168:171], v[138:139], off nt
	global_load_dwordx4 v[172:175], v[140:141], off nt
	global_load_dwordx4 v[176:179], v[138:139], off offset:512 nt
	global_load_dwordx4 v[180:183], v[140:141], off offset:512 nt
	s_mov_b64 s[96:97], 0x10000
	v_lshl_add_u64 v[142:143], v[132:133], 0, s[96:97]
	v_lshl_add_u64 v[144:145], v[136:137], 0, s[96:97]
	global_load_dwordx4 v[184:187], v[142:143], off nt
	global_load_dwordx4 v[188:191], v[144:145], off nt
	global_load_dwordx4 v[192:195], v[142:143], off offset:512 nt
	global_load_dwordx4 v[196:199], v[144:145], off offset:512 nt
	s_mov_b64 s[96:97], 0x20000
	v_lshl_add_u64 v[146:147], v[132:133], 0, s[96:97]
	v_lshl_add_u64 v[148:149], v[136:137], 0, s[96:97]
	global_load_dwordx4 v[224:227], v[146:147], off nt
	global_load_dwordx4 v[228:231], v[148:149], off nt
	global_load_dwordx4 v[232:235], v[146:147], off offset:512 nt
	global_load_dwordx4 v[236:239], v[148:149], off offset:512 nt
	s_mov_b64 s[96:97], 0x30000
	v_lshl_add_u64 v[150:151], v[132:133], 0, s[96:97]
	v_lshl_add_u64 v[152:153], v[136:137], 0, s[96:97]
	global_load_dwordx4 v[240:243], v[150:151], off nt
	global_load_dwordx4 v[244:247], v[152:153], off nt
	global_load_dwordx4 v[248:251], v[150:151], off offset:512 nt
	global_load_dwordx4 v[206:209], v[152:153], off offset:512 nt
	v_mov_b32_dpp v200, v118 quad_perm:[1,0,3,2] row_mask:0xf bank_mask:0xf
	v_cndmask_b32_dpp v201, v114, v200, vcc quad_perm:[1,0,3,2] row_mask:0xf bank_mask:0xf
	v_cndmask_b32_e32 v118, v201, v118, vcc
	v_cndmask_b32_e32 v114, v114, v201, vcc
	v_mov_b32_dpp v200, v119 quad_perm:[1,0,3,2] row_mask:0xf bank_mask:0xf
	v_cndmask_b32_dpp v201, v115, v200, vcc quad_perm:[1,0,3,2] row_mask:0xf bank_mask:0xf
	v_cndmask_b32_e32 v119, v201, v119, vcc
	v_cndmask_b32_e32 v115, v115, v201, vcc
	v_mov_b32_dpp v200, v120 quad_perm:[1,0,3,2] row_mask:0xf bank_mask:0xf
	v_cndmask_b32_dpp v201, v116, v200, vcc quad_perm:[1,0,3,2] row_mask:0xf bank_mask:0xf
	v_cndmask_b32_e32 v120, v201, v120, vcc
	v_cndmask_b32_e32 v116, v116, v201, vcc
	v_mov_b32_dpp v200, v121 quad_perm:[1,0,3,2] row_mask:0xf bank_mask:0xf
	v_cndmask_b32_dpp v201, v117, v200, vcc quad_perm:[1,0,3,2] row_mask:0xf bank_mask:0xf
	v_cndmask_b32_e32 v121, v201, v121, vcc
	v_cndmask_b32_e32 v117, v117, v201, vcc
	v_mov_b32_dpp v200, v126 quad_perm:[1,0,3,2] row_mask:0xf bank_mask:0xf
	v_cndmask_b32_dpp v201, v122, v200, vcc quad_perm:[1,0,3,2] row_mask:0xf bank_mask:0xf
	v_cndmask_b32_e32 v126, v201, v126, vcc
	v_cndmask_b32_e32 v122, v122, v201, vcc
	v_mov_b32_dpp v200, v127 quad_perm:[1,0,3,2] row_mask:0xf bank_mask:0xf
	v_cndmask_b32_dpp v201, v123, v200, vcc quad_perm:[1,0,3,2] row_mask:0xf bank_mask:0xf
	v_cndmask_b32_e32 v127, v201, v127, vcc
	v_cndmask_b32_e32 v123, v123, v201, vcc
	v_mov_b32_dpp v200, v128 quad_perm:[1,0,3,2] row_mask:0xf bank_mask:0xf
	v_cndmask_b32_dpp v201, v124, v200, vcc quad_perm:[1,0,3,2] row_mask:0xf bank_mask:0xf
	v_cndmask_b32_e32 v128, v201, v128, vcc
	v_cndmask_b32_e32 v124, v124, v201, vcc
	v_mov_b32_dpp v200, v129 quad_perm:[1,0,3,2] row_mask:0xf bank_mask:0xf
	v_cndmask_b32_dpp v201, v125, v200, vcc quad_perm:[1,0,3,2] row_mask:0xf bank_mask:0xf
	v_cndmask_b32_e32 v129, v201, v129, vcc
	v_cndmask_b32_e32 v125, v125, v201, vcc
	s_waitcnt vmcnt(12)
;     ...
; #pragma unroll
;     for (int ai = 0; ai < 2; ++ai)
; #pragma unroll
;       for (int m = 0; m < 4; ++m)
;         epi(brow + ai * HALF + wr * 64 + m * 16 + fr, bcol + wc * 32, fq, acc[ai][0][m][0], acc[ai][0][m][1], acc[ai][1][m][0], acc[ai][1][m][1]);
	v_pk_add_f32 v[168:169], v[118:119], v[168:169]
	v_pk_add_f32 v[170:171], v[120:121], v[170:171]
	v_pk_add_f32 v[172:173], v[114:115], v[172:173]
	v_pk_add_f32 v[174:175], v[116:117], v[174:175]
	v_pk_add_f32 v[176:177], v[126:127], v[176:177]
	v_pk_add_f32 v[178:179], v[128:129], v[178:179]
	v_pk_add_f32 v[180:181], v[122:123], v[180:181]
	v_pk_add_f32 v[182:183], v[124:125], v[182:183]
	v_lshl_add_u64 v[202:203], v[138:139], 0, s[98:99]
	v_lshl_add_u64 v[204:205], v[140:141], 0, s[98:99]
	global_store_dwordx4 v[202:203], v[168:171], off sc1 nt
	global_store_dwordx4 v[204:205], v[172:175], off sc1 nt
	global_store_dwordx4 v[202:203], v[176:179], off offset:512 sc1 nt
	global_store_dwordx4 v[204:205], v[180:183], off offset:512 sc1 nt
	s_nop 1
	s_mov_b64 s[96:97], 0x80000
	v_lshl_add_u64 v[138:139], v[132:133], 0, s[96:97]
	v_lshl_add_u64 v[140:141], v[136:137], 0, s[96:97]
	global_load_dwordx4 v[168:171], v[138:139], off nt
	global_load_dwordx4 v[172:175], v[140:141], off nt
	global_load_dwordx4 v[176:179], v[138:139], off offset:512 nt
	global_load_dwordx4 v[180:183], v[140:141], off offset:512 nt
	v_mov_b32_dpp v200, v102 quad_perm:[1,0,3,2] row_mask:0xf bank_mask:0xf
	v_cndmask_b32_dpp v201, v98, v200, vcc quad_perm:[1,0,3,2] row_mask:0xf bank_mask:0xf
	v_cndmask_b32_e32 v102, v201, v102, vcc
	v_cndmask_b32_e32 v98, v98, v201, vcc
	v_mov_b32_dpp v200, v103 quad_perm:[1,0,3,2] row_mask:0xf bank_mask:0xf
	v_cndmask_b32_dpp v201, v99, v200, vcc quad_perm:[1,0,3,2] row_mask:0xf bank_mask:0xf
	v_cndmask_b32_e32 v103, v201, v103, vcc
	v_cndmask_b32_e32 v99, v99, v201, vcc
	v_mov_b32_dpp v200, v104 quad_perm:[1,0,3,2] row_mask:0xf bank_mask:0xf
	v_cndmask_b32_dpp v201, v100, v200, vcc quad_perm:[1,0,3,2] row_mask:0xf bank_mask:0xf
	v_cndmask_b32_e32 v104, v201, v104, vcc
	v_cndmask_b32_e32 v100, v100, v201, vcc
	v_mov_b32_dpp v200, v105 quad_perm:[1,0,3,2] row_mask:0xf bank_mask:0xf
	v_cndmask_b32_dpp v201, v101, v200, vcc quad_perm:[1,0,3,2] row_mask:0xf bank_mask:0xf
	v_cndmask_b32_e32 v105, v201, v105, vcc
	v_cndmask_b32_e32 v101, v101, v201, vcc
	v_mov_b32_dpp v200, v110 quad_perm:[1,0,3,2] row_mask:0xf bank_mask:0xf
	v_cndmask_b32_dpp v201, v106, v200, vcc quad_perm:[1,0,3,2] row_mask:0xf bank_mask:0xf
	v_cndmask_b32_e32 v110, v201, v110, vcc
	v_cndmask_b32_e32 v106, v106, v201, vcc
	v_mov_b32_dpp v200, v111 quad_perm:[1,0,3,2] row_mask:0xf bank_mask:0xf
	v_cndmask_b32_dpp v201, v107, v200, vcc quad_perm:[1,0,3,2] row_mask:0xf bank_mask:0xf
	v_cndmask_b32_e32 v111, v201, v111, vcc
	v_cndmask_b32_e32 v107, v107, v201, vcc
	v_mov_b32_dpp v200, v112 quad_perm:[1,0,3,2] row_mask:0xf bank_mask:0xf
	v_cndmask_b32_dpp v201, v108, v200, vcc quad_perm:[1,0,3,2] row_mask:0xf bank_mask:0xf
	v_cndmask_b32_e32 v112, v201, v112, vcc
	v_cndmask_b32_e32 v108, v108, v201, vcc
	v_mov_b32_dpp v200, v113 quad_perm:[1,0,3,2] row_mask:0xf bank_mask:0xf
	v_cndmask_b32_dpp v201, v109, v200, vcc quad_perm:[1,0,3,2] row_mask:0xf bank_mask:0xf
	v_cndmask_b32_e32 v113, v201, v113, vcc
	v_cndmask_b32_e32 v109, v109, v201, vcc
	s_waitcnt vmcnt(16)
	v_pk_add_f32 v[184:185], v[102:103], v[184:185]
	v_pk_add_f32 v[186:187], v[104:105], v[186:187]
	v_pk_add_f32 v[188:189], v[98:99], v[188:189]
	v_pk_add_f32 v[190:191], v[100:101], v[190:191]
	v_pk_add_f32 v[192:193], v[110:111], v[192:193]
	v_pk_add_f32 v[194:195], v[112:113], v[194:195]
	v_pk_add_f32 v[196:197], v[106:107], v[196:197]
	v_pk_add_f32 v[198:199], v[108:109], v[198:199]
	v_lshl_add_u64 v[202:203], v[142:143], 0, s[98:99]
	v_lshl_add_u64 v[204:205], v[144:145], 0, s[98:99]
	global_store_dwordx4 v[202:203], v[184:187], off sc1 nt
	global_store_dwordx4 v[204:205], v[188:191], off sc1 nt
	global_store_dwordx4 v[202:203], v[192:195], off offset:512 sc1 nt
	global_store_dwordx4 v[204:205], v[196:199], off offset:512 sc1 nt
	s_nop 1
	s_mov_b64 s[96:97], 0x90000
	v_lshl_add_u64 v[142:143], v[132:133], 0, s[96:97]
	v_lshl_add_u64 v[144:145], v[136:137], 0, s[96:97]
	global_load_dwordx4 v[184:187], v[142:143], off nt
	global_load_dwordx4 v[188:191], v[144:145], off nt
	global_load_dwordx4 v[192:195], v[142:143], off offset:512 nt
	global_load_dwordx4 v[196:199], v[144:145], off offset:512 nt
	v_mov_b32_dpp v200, v86 quad_perm:[1,0,3,2] row_mask:0xf bank_mask:0xf
	v_cndmask_b32_dpp v201, v82, v200, vcc quad_perm:[1,0,3,2] row_mask:0xf bank_mask:0xf
	v_cndmask_b32_e32 v86, v201, v86, vcc
	v_cndmask_b32_e32 v82, v82, v201, vcc
	v_mov_b32_dpp v200, v87 quad_perm:[1,0,3,2] row_mask:0xf bank_mask:0xf
	v_cndmask_b32_dpp v201, v83, v200, vcc quad_perm:[1,0,3,2] row_mask:0xf bank_mask:0xf
	v_cndmask_b32_e32 v87, v201, v87, vcc
	v_cndmask_b32_e32 v83, v83, v201, vcc
	v_mov_b32_dpp v200, v88 quad_perm:[1,0,3,2] row_mask:0xf bank_mask:0xf
	v_cndmask_b32_dpp v201, v84, v200, vcc quad_perm:[1,0,3,2] row_mask:0xf bank_mask:0xf
	v_cndmask_b32_e32 v88, v201, v88, vcc
	v_cndmask_b32_e32 v84, v84, v201, vcc
	v_mov_b32_dpp v200, v89 quad_perm:[1,0,3,2] row_mask:0xf bank_mask:0xf
	v_cndmask_b32_dpp v201, v85, v200, vcc quad_perm:[1,0,3,2] row_mask:0xf bank_mask:0xf
	v_cndmask_b32_e32 v89, v201, v89, vcc
	v_cndmask_b32_e32 v85, v85, v201, vcc
	v_mov_b32_dpp v200, v94 quad_perm:[1,0,3,2] row_mask:0xf bank_mask:0xf
	v_cndmask_b32_dpp v201, v90, v200, vcc quad_perm:[1,0,3,2] row_mask:0xf bank_mask:0xf
	v_cndmask_b32_e32 v94, v201, v94, vcc
	v_cndmask_b32_e32 v90, v90, v201, vcc
	v_mov_b32_dpp v200, v95 quad_perm:[1,0,3,2] row_mask:0xf bank_mask:0xf
	v_cndmask_b32_dpp v201, v91, v200, vcc quad_perm:[1,0,3,2] row_mask:0xf bank_mask:0xf
	v_cndmask_b32_e32 v95, v201, v95, vcc
	v_cndmask_b32_e32 v91, v91, v201, vcc
	v_mov_b32_dpp v200, v96 quad_perm:[1,0,3,2] row_mask:0xf bank_mask:0xf
	v_cndmask_b32_dpp v201, v92, v200, vcc quad_perm:[1,0,3,2] row_mask:0xf bank_mask:0xf
	v_cndmask_b32_e32 v96, v201, v96, vcc
	v_cndmask_b32_e32 v92, v92, v201, vcc
	v_mov_b32_dpp v200, v97 quad_perm:[1,0,3,2] row_mask:0xf bank_mask:0xf
	v_cndmask_b32_dpp v201, v93, v200, vcc quad_perm:[1,0,3,2] row_mask:0xf bank_mask:0xf
	v_cndmask_b32_e32 v97, v201, v97, vcc
	v_cndmask_b32_e32 v93, v93, v201, vcc
	s_waitcnt vmcnt(20)
;     ...
; #pragma unroll
;     for (int ai = 0; ai < 2; ++ai)
; #pragma unroll
;       for (int m = 0; m < 4; ++m)
;         epi(brow + ai * HALF + wr * 64 + m * 16 + fr, bcol + wc * 32, fq, acc[ai][0][m][0], acc[ai][0][m][1], acc[ai][1][m][0], acc[ai][1][m][1]);
	v_pk_add_f32 v[224:225], v[86:87], v[224:225]
	v_pk_add_f32 v[226:227], v[88:89], v[226:227]
	v_pk_add_f32 v[228:229], v[82:83], v[228:229]
	v_pk_add_f32 v[230:231], v[84:85], v[230:231]
	v_pk_add_f32 v[232:233], v[94:95], v[232:233]
	v_pk_add_f32 v[234:235], v[96:97], v[234:235]
	v_pk_add_f32 v[236:237], v[90:91], v[236:237]
	v_pk_add_f32 v[238:239], v[92:93], v[238:239]
	v_lshl_add_u64 v[202:203], v[146:147], 0, s[98:99]
	v_lshl_add_u64 v[204:205], v[148:149], 0, s[98:99]
	global_store_dwordx4 v[202:203], v[224:227], off sc1 nt
	global_store_dwordx4 v[204:205], v[228:231], off sc1 nt
	global_store_dwordx4 v[202:203], v[232:235], off offset:512 sc1 nt
	global_store_dwordx4 v[204:205], v[236:239], off offset:512 sc1 nt
	s_nop 1
	s_mov_b64 s[96:97], 0xa0000
	v_lshl_add_u64 v[146:147], v[132:133], 0, s[96:97]
	v_lshl_add_u64 v[148:149], v[136:137], 0, s[96:97]
	global_load_dwordx4 v[224:227], v[146:147], off nt
	global_load_dwordx4 v[228:231], v[148:149], off nt
	global_load_dwordx4 v[232:235], v[146:147], off offset:512 nt
	global_load_dwordx4 v[236:239], v[148:149], off offset:512 nt
	v_mov_b32_dpp v200, v70 quad_perm:[1,0,3,2] row_mask:0xf bank_mask:0xf
	v_cndmask_b32_dpp v201, v66, v200, vcc quad_perm:[1,0,3,2] row_mask:0xf bank_mask:0xf
	v_cndmask_b32_e32 v70, v201, v70, vcc
	v_cndmask_b32_e32 v66, v66, v201, vcc
	v_mov_b32_dpp v200, v71 quad_perm:[1,0,3,2] row_mask:0xf bank_mask:0xf
	v_cndmask_b32_dpp v201, v67, v200, vcc quad_perm:[1,0,3,2] row_mask:0xf bank_mask:0xf
	v_cndmask_b32_e32 v71, v201, v71, vcc
	v_cndmask_b32_e32 v67, v67, v201, vcc
	v_mov_b32_dpp v200, v72 quad_perm:[1,0,3,2] row_mask:0xf bank_mask:0xf
	v_cndmask_b32_dpp v201, v68, v200, vcc quad_perm:[1,0,3,2] row_mask:0xf bank_mask:0xf
	v_cndmask_b32_e32 v72, v201, v72, vcc
	v_cndmask_b32_e32 v68, v68, v201, vcc
	v_mov_b32_dpp v200, v73 quad_perm:[1,0,3,2] row_mask:0xf bank_mask:0xf
	v_cndmask_b32_dpp v201, v69, v200, vcc quad_perm:[1,0,3,2] row_mask:0xf bank_mask:0xf
	v_cndmask_b32_e32 v73, v201, v73, vcc
	v_cndmask_b32_e32 v69, v69, v201, vcc
	v_mov_b32_dpp v200, v78 quad_perm:[1,0,3,2] row_mask:0xf bank_mask:0xf
	v_cndmask_b32_dpp v201, v74, v200, vcc quad_perm:[1,0,3,2] row_mask:0xf bank_mask:0xf
	v_cndmask_b32_e32 v78, v201, v78, vcc
	v_cndmask_b32_e32 v74, v74, v201, vcc
	v_mov_b32_dpp v200, v79 quad_perm:[1,0,3,2] row_mask:0xf bank_mask:0xf
	v_cndmask_b32_dpp v201, v75, v200, vcc quad_perm:[1,0,3,2] row_mask:0xf bank_mask:0xf
	v_cndmask_b32_e32 v79, v201, v79, vcc
	v_cndmask_b32_e32 v75, v75, v201, vcc
	v_mov_b32_dpp v200, v80 quad_perm:[1,0,3,2] row_mask:0xf bank_mask:0xf
	v_cndmask_b32_dpp v201, v76, v200, vcc quad_perm:[1,0,3,2] row_mask:0xf bank_mask:0xf
	v_cndmask_b32_e32 v80, v201, v80, vcc
	v_cndmask_b32_e32 v76, v76, v201, vcc
	v_mov_b32_dpp v200, v81 quad_perm:[1,0,3,2] row_mask:0xf bank_mask:0xf
	v_cndmask_b32_dpp v201, v77, v200, vcc quad_perm:[1,0,3,2] row_mask:0xf bank_mask:0xf
	v_cndmask_b32_e32 v81, v201, v81, vcc
	v_cndmask_b32_e32 v77, v77, v201, vcc
	s_waitcnt vmcnt(24)
	v_pk_add_f32 v[240:241], v[70:71], v[240:241]
	v_pk_add_f32 v[242:243], v[72:73], v[242:243]
	v_pk_add_f32 v[244:245], v[66:67], v[244:245]
	v_pk_add_f32 v[246:247], v[68:69], v[246:247]
	v_pk_add_f32 v[248:249], v[78:79], v[248:249]
	v_pk_add_f32 v[250:251], v[80:81], v[250:251]
	v_pk_add_f32 v[206:207], v[74:75], v[206:207]
	v_pk_add_f32 v[208:209], v[76:77], v[208:209]
	v_lshl_add_u64 v[202:203], v[150:151], 0, s[98:99]
	v_lshl_add_u64 v[204:205], v[152:153], 0, s[98:99]
	global_store_dwordx4 v[202:203], v[240:243], off sc1 nt
	global_store_dwordx4 v[204:205], v[244:247], off sc1 nt
	global_store_dwordx4 v[202:203], v[248:251], off offset:512 sc1 nt
	global_store_dwordx4 v[204:205], v[206:209], off offset:512 sc1 nt
	s_nop 1
	s_mov_b64 s[96:97], 0xb0000
	v_lshl_add_u64 v[150:151], v[132:133], 0, s[96:97]
	v_lshl_add_u64 v[152:153], v[136:137], 0, s[96:97]
	global_load_dwordx4 v[240:243], v[150:151], off nt
	global_load_dwordx4 v[244:247], v[152:153], off nt
	global_load_dwordx4 v[248:251], v[150:151], off offset:512 nt
	global_load_dwordx4 v[206:209], v[152:153], off offset:512 nt
	v_mov_b32_dpp v200, v54 quad_perm:[1,0,3,2] row_mask:0xf bank_mask:0xf
	v_cndmask_b32_dpp v201, v50, v200, vcc quad_perm:[1,0,3,2] row_mask:0xf bank_mask:0xf
	v_cndmask_b32_e32 v54, v201, v54, vcc
	v_cndmask_b32_e32 v50, v50, v201, vcc
	v_mov_b32_dpp v200, v55 quad_perm:[1,0,3,2] row_mask:0xf bank_mask:0xf
	v_cndmask_b32_dpp v201, v51, v200, vcc quad_perm:[1,0,3,2] row_mask:0xf bank_mask:0xf
	v_cndmask_b32_e32 v55, v201, v55, vcc
	v_cndmask_b32_e32 v51, v51, v201, vcc
	v_mov_b32_dpp v200, v56 quad_perm:[1,0,3,2] row_mask:0xf bank_mask:0xf
	v_cndmask_b32_dpp v201, v52, v200, vcc quad_perm:[1,0,3,2] row_mask:0xf bank_mask:0xf
	v_cndmask_b32_e32 v56, v201, v56, vcc
	v_cndmask_b32_e32 v52, v52, v201, vcc
	v_mov_b32_dpp v200, v57 quad_perm:[1,0,3,2] row_mask:0xf bank_mask:0xf
	v_cndmask_b32_dpp v201, v53, v200, vcc quad_perm:[1,0,3,2] row_mask:0xf bank_mask:0xf
	v_cndmask_b32_e32 v57, v201, v57, vcc
	v_cndmask_b32_e32 v53, v53, v201, vcc
	v_mov_b32_dpp v200, v62 quad_perm:[1,0,3,2] row_mask:0xf bank_mask:0xf
	v_cndmask_b32_dpp v201, v58, v200, vcc quad_perm:[1,0,3,2] row_mask:0xf bank_mask:0xf
	v_cndmask_b32_e32 v62, v201, v62, vcc
	v_cndmask_b32_e32 v58, v58, v201, vcc
	v_mov_b32_dpp v200, v63 quad_perm:[1,0,3,2] row_mask:0xf bank_mask:0xf
	v_cndmask_b32_dpp v201, v59, v200, vcc quad_perm:[1,0,3,2] row_mask:0xf bank_mask:0xf
	v_cndmask_b32_e32 v63, v201, v63, vcc
	v_cndmask_b32_e32 v59, v59, v201, vcc
	v_mov_b32_dpp v200, v64 quad_perm:[1,0,3,2] row_mask:0xf bank_mask:0xf
	v_cndmask_b32_dpp v201, v60, v200, vcc quad_perm:[1,0,3,2] row_mask:0xf bank_mask:0xf
	v_cndmask_b32_e32 v64, v201, v64, vcc
	v_cndmask_b32_e32 v60, v60, v201, vcc
	v_mov_b32_dpp v200, v65 quad_perm:[1,0,3,2] row_mask:0xf bank_mask:0xf
	v_cndmask_b32_dpp v201, v61, v200, vcc quad_perm:[1,0,3,2] row_mask:0xf bank_mask:0xf
	v_cndmask_b32_e32 v65, v201, v65, vcc
	v_cndmask_b32_e32 v61, v61, v201, vcc
	s_waitcnt vmcnt(24)
;     ...
; #pragma unroll
;     for (int ai = 0; ai < 2; ++ai)
; #pragma unroll
;       for (int m = 0; m < 4; ++m)
;         epi(brow + ai * HALF + wr * 64 + m * 16 + fr, bcol + wc * 32, fq, acc[ai][0][m][0], acc[ai][0][m][1], acc[ai][1][m][0], acc[ai][1][m][1]);
	v_pk_add_f32 v[168:169], v[54:55], v[168:169]
	v_pk_add_f32 v[170:171], v[56:57], v[170:171]
	v_pk_add_f32 v[172:173], v[50:51], v[172:173]
	v_pk_add_f32 v[174:175], v[52:53], v[174:175]
	v_pk_add_f32 v[176:177], v[62:63], v[176:177]
	v_pk_add_f32 v[178:179], v[64:65], v[178:179]
	v_pk_add_f32 v[180:181], v[58:59], v[180:181]
	v_pk_add_f32 v[182:183], v[60:61], v[182:183]
	v_lshl_add_u64 v[202:203], v[138:139], 0, s[98:99]
	v_lshl_add_u64 v[204:205], v[140:141], 0, s[98:99]
	global_store_dwordx4 v[202:203], v[168:171], off sc1 nt
	global_store_dwordx4 v[204:205], v[172:175], off sc1 nt
	global_store_dwordx4 v[202:203], v[176:179], off offset:512 sc1 nt
	global_store_dwordx4 v[204:205], v[180:183], off offset:512 sc1 nt
	v_mov_b32_dpp v200, v38 quad_perm:[1,0,3,2] row_mask:0xf bank_mask:0xf
	v_cndmask_b32_dpp v201, v34, v200, vcc quad_perm:[1,0,3,2] row_mask:0xf bank_mask:0xf
	v_cndmask_b32_e32 v38, v201, v38, vcc
	v_cndmask_b32_e32 v34, v34, v201, vcc
	v_mov_b32_dpp v200, v39 quad_perm:[1,0,3,2] row_mask:0xf bank_mask:0xf
	v_cndmask_b32_dpp v201, v35, v200, vcc quad_perm:[1,0,3,2] row_mask:0xf bank_mask:0xf
	v_cndmask_b32_e32 v39, v201, v39, vcc
	v_cndmask_b32_e32 v35, v35, v201, vcc
	v_mov_b32_dpp v200, v40 quad_perm:[1,0,3,2] row_mask:0xf bank_mask:0xf
	v_cndmask_b32_dpp v201, v36, v200, vcc quad_perm:[1,0,3,2] row_mask:0xf bank_mask:0xf
	v_cndmask_b32_e32 v40, v201, v40, vcc
	v_cndmask_b32_e32 v36, v36, v201, vcc
	v_mov_b32_dpp v200, v41 quad_perm:[1,0,3,2] row_mask:0xf bank_mask:0xf
	v_cndmask_b32_dpp v201, v37, v200, vcc quad_perm:[1,0,3,2] row_mask:0xf bank_mask:0xf
	v_cndmask_b32_e32 v41, v201, v41, vcc
	v_cndmask_b32_e32 v37, v37, v201, vcc
	v_mov_b32_dpp v200, v46 quad_perm:[1,0,3,2] row_mask:0xf bank_mask:0xf
	v_cndmask_b32_dpp v201, v42, v200, vcc quad_perm:[1,0,3,2] row_mask:0xf bank_mask:0xf
	v_cndmask_b32_e32 v46, v201, v46, vcc
	v_cndmask_b32_e32 v42, v42, v201, vcc
	v_mov_b32_dpp v200, v47 quad_perm:[1,0,3,2] row_mask:0xf bank_mask:0xf
	v_cndmask_b32_dpp v201, v43, v200, vcc quad_perm:[1,0,3,2] row_mask:0xf bank_mask:0xf
	v_cndmask_b32_e32 v47, v201, v47, vcc
	v_cndmask_b32_e32 v43, v43, v201, vcc
	v_mov_b32_dpp v200, v48 quad_perm:[1,0,3,2] row_mask:0xf bank_mask:0xf
	v_cndmask_b32_dpp v201, v44, v200, vcc quad_perm:[1,0,3,2] row_mask:0xf bank_mask:0xf
	v_cndmask_b32_e32 v48, v201, v48, vcc
	v_cndmask_b32_e32 v44, v44, v201, vcc
	v_mov_b32_dpp v200, v49 quad_perm:[1,0,3,2] row_mask:0xf bank_mask:0xf
	v_cndmask_b32_dpp v201, v45, v200, vcc quad_perm:[1,0,3,2] row_mask:0xf bank_mask:0xf
	v_cndmask_b32_e32 v49, v201, v49, vcc
	v_cndmask_b32_e32 v45, v45, v201, vcc
	s_waitcnt vmcnt(20)
	v_pk_add_f32 v[184:185], v[38:39], v[184:185]
	v_pk_add_f32 v[186:187], v[40:41], v[186:187]
	v_pk_add_f32 v[188:189], v[34:35], v[188:189]
	v_pk_add_f32 v[190:191], v[36:37], v[190:191]
	v_pk_add_f32 v[192:193], v[46:47], v[192:193]
	v_pk_add_f32 v[194:195], v[48:49], v[194:195]
	v_pk_add_f32 v[196:197], v[42:43], v[196:197]
	v_pk_add_f32 v[198:199], v[44:45], v[198:199]
	v_lshl_add_u64 v[202:203], v[142:143], 0, s[98:99]
	v_lshl_add_u64 v[204:205], v[144:145], 0, s[98:99]
	global_store_dwordx4 v[202:203], v[184:187], off sc1 nt
	global_store_dwordx4 v[204:205], v[188:191], off sc1 nt
	global_store_dwordx4 v[202:203], v[192:195], off offset:512 sc1 nt
	global_store_dwordx4 v[204:205], v[196:199], off offset:512 sc1 nt
	v_mov_b32_dpp v200, v22 quad_perm:[1,0,3,2] row_mask:0xf bank_mask:0xf
	v_cndmask_b32_dpp v201, v220, v200, vcc quad_perm:[1,0,3,2] row_mask:0xf bank_mask:0xf
	v_cndmask_b32_e32 v22, v201, v22, vcc
	v_cndmask_b32_e32 v220, v220, v201, vcc
	v_mov_b32_dpp v200, v23 quad_perm:[1,0,3,2] row_mask:0xf bank_mask:0xf
	v_cndmask_b32_dpp v201, v221, v200, vcc quad_perm:[1,0,3,2] row_mask:0xf bank_mask:0xf
	v_cndmask_b32_e32 v23, v201, v23, vcc
	v_cndmask_b32_e32 v221, v221, v201, vcc
	v_mov_b32_dpp v200, v24 quad_perm:[1,0,3,2] row_mask:0xf bank_mask:0xf
	v_cndmask_b32_dpp v201, v222, v200, vcc quad_perm:[1,0,3,2] row_mask:0xf bank_mask:0xf
	v_cndmask_b32_e32 v24, v201, v24, vcc
	v_cndmask_b32_e32 v222, v222, v201, vcc
	v_mov_b32_dpp v200, v25 quad_perm:[1,0,3,2] row_mask:0xf bank_mask:0xf
	v_cndmask_b32_dpp v201, v223, v200, vcc quad_perm:[1,0,3,2] row_mask:0xf bank_mask:0xf
	v_cndmask_b32_e32 v25, v201, v25, vcc
	v_cndmask_b32_e32 v223, v223, v201, vcc
	v_mov_b32_dpp v200, v30 quad_perm:[1,0,3,2] row_mask:0xf bank_mask:0xf
	v_cndmask_b32_dpp v201, v26, v200, vcc quad_perm:[1,0,3,2] row_mask:0xf bank_mask:0xf
	v_cndmask_b32_e32 v30, v201, v30, vcc
	v_cndmask_b32_e32 v26, v26, v201, vcc
	v_mov_b32_dpp v200, v31 quad_perm:[1,0,3,2] row_mask:0xf bank_mask:0xf
	v_cndmask_b32_dpp v201, v27, v200, vcc quad_perm:[1,0,3,2] row_mask:0xf bank_mask:0xf
	v_cndmask_b32_e32 v31, v201, v31, vcc
	v_cndmask_b32_e32 v27, v27, v201, vcc
	v_mov_b32_dpp v200, v32 quad_perm:[1,0,3,2] row_mask:0xf bank_mask:0xf
	v_cndmask_b32_dpp v201, v28, v200, vcc quad_perm:[1,0,3,2] row_mask:0xf bank_mask:0xf
	v_cndmask_b32_e32 v32, v201, v32, vcc
	v_cndmask_b32_e32 v28, v28, v201, vcc
	v_mov_b32_dpp v200, v33 quad_perm:[1,0,3,2] row_mask:0xf bank_mask:0xf
	v_cndmask_b32_dpp v201, v29, v200, vcc quad_perm:[1,0,3,2] row_mask:0xf bank_mask:0xf
	v_cndmask_b32_e32 v33, v201, v33, vcc
	v_cndmask_b32_e32 v29, v29, v201, vcc
	s_waitcnt vmcnt(16)
; #define WAIT_V(n) asm volatile("s_waitcnt vmcnt(" #n ")" ::: "memory")
;     ...
; #pragma unroll
;     for (int ai = 0; ai < 2; ++ai)
; #pragma unroll
;       for (int m = 0; m < 4; ++m)
;         epi(brow + ai * HALF + wr * 64 + m * 16 + fr, bcol + wc * 32, fq, acc[ai][0][m][0], acc[ai][0][m][1], acc[ai][1][m][0], acc[ai][1][m][1]);
;   }
;   if (!have_next) { WAIT_V(0); __syncthreads(); }
	v_pk_add_f32 v[224:225], v[22:23], v[224:225]
	v_pk_add_f32 v[226:227], v[24:25], v[226:227]
	v_pk_add_f32 v[228:229], v[220:221], v[228:229]
	v_pk_add_f32 v[230:231], v[222:223], v[230:231]
	v_pk_add_f32 v[232:233], v[30:31], v[232:233]
	v_pk_add_f32 v[234:235], v[32:33], v[234:235]
	v_pk_add_f32 v[236:237], v[26:27], v[236:237]
	v_pk_add_f32 v[238:239], v[28:29], v[238:239]
	v_lshl_add_u64 v[202:203], v[146:147], 0, s[98:99]
	v_lshl_add_u64 v[204:205], v[148:149], 0, s[98:99]
	global_store_dwordx4 v[202:203], v[224:227], off sc1 nt
	global_store_dwordx4 v[204:205], v[228:231], off sc1 nt
	global_store_dwordx4 v[202:203], v[232:235], off offset:512 sc1 nt
	global_store_dwordx4 v[204:205], v[236:239], off offset:512 sc1 nt
	v_mov_b32_dpp v200, v6 quad_perm:[1,0,3,2] row_mask:0xf bank_mask:0xf
	v_cndmask_b32_dpp v201, v2, v200, vcc quad_perm:[1,0,3,2] row_mask:0xf bank_mask:0xf
	v_cndmask_b32_e32 v6, v201, v6, vcc
	v_cndmask_b32_e32 v2, v2, v201, vcc
	v_mov_b32_dpp v200, v7 quad_perm:[1,0,3,2] row_mask:0xf bank_mask:0xf
	v_cndmask_b32_dpp v201, v3, v200, vcc quad_perm:[1,0,3,2] row_mask:0xf bank_mask:0xf
	v_cndmask_b32_e32 v7, v201, v7, vcc
	v_cndmask_b32_e32 v3, v3, v201, vcc
	v_mov_b32_dpp v200, v8 quad_perm:[1,0,3,2] row_mask:0xf bank_mask:0xf
	v_cndmask_b32_dpp v201, v4, v200, vcc quad_perm:[1,0,3,2] row_mask:0xf bank_mask:0xf
	v_cndmask_b32_e32 v8, v201, v8, vcc
	v_cndmask_b32_e32 v4, v4, v201, vcc
	v_mov_b32_dpp v200, v9 quad_perm:[1,0,3,2] row_mask:0xf bank_mask:0xf
	v_cndmask_b32_dpp v201, v5, v200, vcc quad_perm:[1,0,3,2] row_mask:0xf bank_mask:0xf
	v_cndmask_b32_e32 v9, v201, v9, vcc
	v_cndmask_b32_e32 v5, v5, v201, vcc
	v_mov_b32_dpp v200, v14 quad_perm:[1,0,3,2] row_mask:0xf bank_mask:0xf
	v_cndmask_b32_dpp v201, v10, v200, vcc quad_perm:[1,0,3,2] row_mask:0xf bank_mask:0xf
	v_cndmask_b32_e32 v14, v201, v14, vcc
	v_cndmask_b32_e32 v10, v10, v201, vcc
	v_mov_b32_dpp v200, v15 quad_perm:[1,0,3,2] row_mask:0xf bank_mask:0xf
	v_cndmask_b32_dpp v201, v11, v200, vcc quad_perm:[1,0,3,2] row_mask:0xf bank_mask:0xf
	v_cndmask_b32_e32 v15, v201, v15, vcc
	v_cndmask_b32_e32 v11, v11, v201, vcc
	v_mov_b32_dpp v200, v16 quad_perm:[1,0,3,2] row_mask:0xf bank_mask:0xf
	v_cndmask_b32_dpp v201, v12, v200, vcc quad_perm:[1,0,3,2] row_mask:0xf bank_mask:0xf
	v_cndmask_b32_e32 v16, v201, v16, vcc
	v_cndmask_b32_e32 v12, v12, v201, vcc
	v_mov_b32_dpp v200, v17 quad_perm:[1,0,3,2] row_mask:0xf bank_mask:0xf
	v_cndmask_b32_dpp v201, v13, v200, vcc quad_perm:[1,0,3,2] row_mask:0xf bank_mask:0xf
	v_cndmask_b32_e32 v17, v201, v17, vcc
	v_cndmask_b32_e32 v13, v13, v201, vcc
	s_waitcnt vmcnt(12)
	v_pk_add_f32 v[240:241], v[6:7], v[240:241]
	v_pk_add_f32 v[242:243], v[8:9], v[242:243]
	v_pk_add_f32 v[244:245], v[2:3], v[244:245]
	v_pk_add_f32 v[246:247], v[4:5], v[246:247]
	v_pk_add_f32 v[248:249], v[14:15], v[248:249]
	v_pk_add_f32 v[250:251], v[16:17], v[250:251]
	v_pk_add_f32 v[206:207], v[10:11], v[206:207]
	v_pk_add_f32 v[208:209], v[12:13], v[208:209]
	v_lshl_add_u64 v[202:203], v[150:151], 0, s[98:99]
	v_lshl_add_u64 v[204:205], v[152:153], 0, s[98:99]
	global_store_dwordx4 v[202:203], v[240:243], off sc1 nt
	global_store_dwordx4 v[204:205], v[244:247], off sc1 nt
	global_store_dwordx4 v[202:203], v[248:251], off offset:512 sc1 nt
	global_store_dwordx4 v[204:205], v[206:209], off offset:512 sc1 nt
	s_andn2_b64 vcc, exec, s[4:5]
	s_cbranch_vccnz .LBB0_1474
	s_waitcnt vmcnt(0)
	s_waitcnt lgkmcnt(0)
	s_barrier
	s_branch .LBB0_1474

;     ...
; #pragma unroll
;     for (int ai = 0; ai < 2; ++ai)
; #pragma unroll
;       for (int m = 0; m < 4; ++m)
;         epi(brow + ai * HALF + wr * 64 + m * 16 + fr, bcol + wc * 32, fq, acc[ai][0][m][0], acc[ai][0][m][1], acc[ai][1][m][0], acc[ai][1][m][1]);
.LBB0_1564:
	v_or_b32_e32 v0, s16, v140
	v_add_u32_e32 v136, v0, v141
	v_ashrrev_i32_e32 v137, 31, v136
	v_readlane_b32 s4, v253, 60
	v_lshl_or_b32 v0, v139, 5, s15
	v_lshlrev_b64 v[132:133], 12, v[136:137]
	v_readlane_b32 s5, v253, 61
	v_lshlrev_b64 v[134:135], 2, v[0:1]
	v_mov_b32_e32 v131, v1
	v_lshl_add_u64 v[132:133], s[4:5], 0, v[132:133]
	v_lshl_add_u64 v[132:133], v[132:133], 0, v[134:135]
	v_lshl_add_u64 v[132:133], v[132:133], 0, v[130:131]
	v_cndmask_b32_e64 v0, 0, 1, s[2:3]
	v_and_b32_e32 v134, 1, v210
	v_cmp_eq_u32_e32 vcc, 0, v134
	s_nop 1
	v_mov_b32_e32 v135, 0xfffff040
	v_cndmask_b32_e32 v134, v135, v1, vcc
	v_cndmask_b32_e32 v135, -1, v1, vcc
	v_lshl_add_u64 v[132:133], v[132:133], 0, v[134:135]
	s_mov_b64 s[4:5], 0x1000
	v_lshl_add_u64 v[136:137], v[132:133], 0, s[4:5]
	v_mov_b64_e32 v[138:139], v[132:133]
	v_mov_b64_e32 v[140:141], v[136:137]
	global_load_dwordx4 v[168:171], v[138:139], off nt
	global_load_dwordx4 v[172:175], v[140:141], off nt
	global_load_dwordx4 v[176:179], v[138:139], off offset:512 nt
	global_load_dwordx4 v[180:183], v[140:141], off offset:512 nt
	s_mov_b64 s[4:5], 0x10000
	v_lshl_add_u64 v[142:143], v[132:133], 0, s[4:5]
	v_lshl_add_u64 v[144:145], v[136:137], 0, s[4:5]
	global_load_dwordx4 v[184:187], v[142:143], off nt
	global_load_dwordx4 v[188:191], v[144:145], off nt
	global_load_dwordx4 v[192:195], v[142:143], off offset:512 nt
	global_load_dwordx4 v[196:199], v[144:145], off offset:512 nt
	s_mov_b64 s[4:5], 0x20000
	v_lshl_add_u64 v[146:147], v[132:133], 0, s[4:5]
	v_lshl_add_u64 v[148:149], v[136:137], 0, s[4:5]
	global_load_dwordx4 v[220:223], v[146:147], off nt
	global_load_dwordx4 v[224:227], v[148:149], off nt
	global_load_dwordx4 v[228:231], v[146:147], off offset:512 nt
	global_load_dwordx4 v[232:235], v[148:149], off offset:512 nt
	s_mov_b64 s[4:5], 0x30000
	v_lshl_add_u64 v[150:151], v[132:133], 0, s[4:5]
	v_lshl_add_u64 v[152:153], v[136:137], 0, s[4:5]
	global_load_dwordx4 v[236:239], v[150:151], off nt
	global_load_dwordx4 v[240:243], v[152:153], off nt
	global_load_dwordx4 v[244:247], v[150:151], off offset:512 nt
	global_load_dwordx4 v[248:251], v[152:153], off offset:512 nt
	v_mov_b32_dpp v200, v118 quad_perm:[1,0,3,2] row_mask:0xf bank_mask:0xf
	v_cndmask_b32_dpp v201, v114, v200, vcc quad_perm:[1,0,3,2] row_mask:0xf bank_mask:0xf
	v_cndmask_b32_e32 v118, v201, v118, vcc
	v_cndmask_b32_e32 v114, v114, v201, vcc
	v_mov_b32_dpp v200, v119 quad_perm:[1,0,3,2] row_mask:0xf bank_mask:0xf
	v_cndmask_b32_dpp v201, v115, v200, vcc quad_perm:[1,0,3,2] row_mask:0xf bank_mask:0xf
	v_cndmask_b32_e32 v119, v201, v119, vcc
	v_cndmask_b32_e32 v115, v115, v201, vcc
	v_mov_b32_dpp v200, v120 quad_perm:[1,0,3,2] row_mask:0xf bank_mask:0xf
	v_cndmask_b32_dpp v201, v116, v200, vcc quad_perm:[1,0,3,2] row_mask:0xf bank_mask:0xf
	v_cndmask_b32_e32 v120, v201, v120, vcc
	v_cndmask_b32_e32 v116, v116, v201, vcc
	v_mov_b32_dpp v200, v121 quad_perm:[1,0,3,2] row_mask:0xf bank_mask:0xf
	v_cndmask_b32_dpp v201, v117, v200, vcc quad_perm:[1,0,3,2] row_mask:0xf bank_mask:0xf
	v_cndmask_b32_e32 v121, v201, v121, vcc
	v_cndmask_b32_e32 v117, v117, v201, vcc
	v_mov_b32_dpp v200, v126 quad_perm:[1,0,3,2] row_mask:0xf bank_mask:0xf
	v_cndmask_b32_dpp v201, v122, v200, vcc quad_perm:[1,0,3,2] row_mask:0xf bank_mask:0xf
	v_cndmask_b32_e32 v126, v201, v126, vcc
	v_cndmask_b32_e32 v122, v122, v201, vcc
	v_mov_b32_dpp v200, v127 quad_perm:[1,0,3,2] row_mask:0xf bank_mask:0xf
	v_cndmask_b32_dpp v201, v123, v200, vcc quad_perm:[1,0,3,2] row_mask:0xf bank_mask:0xf
	v_cndmask_b32_e32 v127, v201, v127, vcc
	v_cndmask_b32_e32 v123, v123, v201, vcc
	v_mov_b32_dpp v200, v128 quad_perm:[1,0,3,2] row_mask:0xf bank_mask:0xf
	v_cndmask_b32_dpp v201, v124, v200, vcc quad_perm:[1,0,3,2] row_mask:0xf bank_mask:0xf
	v_cndmask_b32_e32 v128, v201, v128, vcc
	v_cndmask_b32_e32 v124, v124, v201, vcc
	v_mov_b32_dpp v200, v129 quad_perm:[1,0,3,2] row_mask:0xf bank_mask:0xf
	v_cndmask_b32_dpp v201, v125, v200, vcc quad_perm:[1,0,3,2] row_mask:0xf bank_mask:0xf
	v_cndmask_b32_e32 v129, v201, v129, vcc
	v_cndmask_b32_e32 v125, v125, v201, vcc
	s_waitcnt vmcnt(12)
	v_pk_add_f32 v[168:169], v[118:119], v[168:169]
	v_pk_add_f32 v[170:171], v[120:121], v[170:171]
	v_pk_add_f32 v[172:173], v[114:115], v[172:173]
	v_pk_add_f32 v[174:175], v[116:117], v[174:175]
	v_pk_add_f32 v[176:177], v[126:127], v[176:177]
	v_pk_add_f32 v[178:179], v[128:129], v[178:179]
	v_pk_add_f32 v[180:181], v[122:123], v[180:181]
	v_pk_add_f32 v[182:183], v[124:125], v[182:183]
	global_store_dwordx4 v[138:139], v[168:171], off sc1 nt
	global_store_dwordx4 v[140:141], v[172:175], off sc1 nt
	global_store_dwordx4 v[138:139], v[176:179], off offset:512 sc1 nt
	global_store_dwordx4 v[140:141], v[180:183], off offset:512 sc1 nt
	s_nop 1
	s_mov_b64 s[4:5], 0x80000
	v_lshl_add_u64 v[138:139], v[132:133], 0, s[4:5]
	v_lshl_add_u64 v[140:141], v[136:137], 0, s[4:5]
	global_load_dwordx4 v[168:171], v[138:139], off nt
	global_load_dwordx4 v[172:175], v[140:141], off nt
	global_load_dwordx4 v[176:179], v[138:139], off offset:512 nt
	global_load_dwordx4 v[180:183], v[140:141], off offset:512 nt
	v_mov_b32_dpp v200, v102 quad_perm:[1,0,3,2] row_mask:0xf bank_mask:0xf
	v_cndmask_b32_dpp v201, v98, v200, vcc quad_perm:[1,0,3,2] row_mask:0xf bank_mask:0xf
	v_cndmask_b32_e32 v102, v201, v102, vcc
	v_cndmask_b32_e32 v98, v98, v201, vcc
	v_mov_b32_dpp v200, v103 quad_perm:[1,0,3,2] row_mask:0xf bank_mask:0xf
	v_cndmask_b32_dpp v201, v99, v200, vcc quad_perm:[1,0,3,2] row_mask:0xf bank_mask:0xf
	v_cndmask_b32_e32 v103, v201, v103, vcc
	v_cndmask_b32_e32 v99, v99, v201, vcc
;     ...
; #pragma unroll
;     for (int ai = 0; ai < 2; ++ai)
; #pragma unroll
;       for (int m = 0; m < 4; ++m)
;         epi(brow + ai * HALF + wr * 64 + m * 16 + fr, bcol + wc * 32, fq, acc[ai][0][m][0], acc[ai][0][m][1], acc[ai][1][m][0], acc[ai][1][m][1]);
	v_mov_b32_dpp v200, v104 quad_perm:[1,0,3,2] row_mask:0xf bank_mask:0xf
	v_cndmask_b32_dpp v201, v100, v200, vcc quad_perm:[1,0,3,2] row_mask:0xf bank_mask:0xf
	v_cndmask_b32_e32 v104, v201, v104, vcc
	v_cndmask_b32_e32 v100, v100, v201, vcc
	v_mov_b32_dpp v200, v105 quad_perm:[1,0,3,2] row_mask:0xf bank_mask:0xf
	v_cndmask_b32_dpp v201, v101, v200, vcc quad_perm:[1,0,3,2] row_mask:0xf bank_mask:0xf
	v_cndmask_b32_e32 v105, v201, v105, vcc
	v_cndmask_b32_e32 v101, v101, v201, vcc
	v_mov_b32_dpp v200, v110 quad_perm:[1,0,3,2] row_mask:0xf bank_mask:0xf
	v_cndmask_b32_dpp v201, v106, v200, vcc quad_perm:[1,0,3,2] row_mask:0xf bank_mask:0xf
	v_cndmask_b32_e32 v110, v201, v110, vcc
	v_cndmask_b32_e32 v106, v106, v201, vcc
	v_mov_b32_dpp v200, v111 quad_perm:[1,0,3,2] row_mask:0xf bank_mask:0xf
	v_cndmask_b32_dpp v201, v107, v200, vcc quad_perm:[1,0,3,2] row_mask:0xf bank_mask:0xf
	v_cndmask_b32_e32 v111, v201, v111, vcc
	v_cndmask_b32_e32 v107, v107, v201, vcc
	v_mov_b32_dpp v200, v112 quad_perm:[1,0,3,2] row_mask:0xf bank_mask:0xf
	v_cndmask_b32_dpp v201, v108, v200, vcc quad_perm:[1,0,3,2] row_mask:0xf bank_mask:0xf
	v_cndmask_b32_e32 v112, v201, v112, vcc
	v_cndmask_b32_e32 v108, v108, v201, vcc
	v_mov_b32_dpp v200, v113 quad_perm:[1,0,3,2] row_mask:0xf bank_mask:0xf
	v_cndmask_b32_dpp v201, v109, v200, vcc quad_perm:[1,0,3,2] row_mask:0xf bank_mask:0xf
	v_cndmask_b32_e32 v113, v201, v113, vcc
	v_cndmask_b32_e32 v109, v109, v201, vcc
	s_waitcnt vmcnt(16)
	v_pk_add_f32 v[184:185], v[102:103], v[184:185]
	v_pk_add_f32 v[186:187], v[104:105], v[186:187]
	v_pk_add_f32 v[188:189], v[98:99], v[188:189]
	v_pk_add_f32 v[190:191], v[100:101], v[190:191]
	v_pk_add_f32 v[192:193], v[110:111], v[192:193]
	v_pk_add_f32 v[194:195], v[112:113], v[194:195]
	v_pk_add_f32 v[196:197], v[106:107], v[196:197]
	v_pk_add_f32 v[198:199], v[108:109], v[198:199]
	global_store_dwordx4 v[142:143], v[184:187], off sc1 nt
	global_store_dwordx4 v[144:145], v[188:191], off sc1 nt
	global_store_dwordx4 v[142:143], v[192:195], off offset:512 sc1 nt
	global_store_dwordx4 v[144:145], v[196:199], off offset:512 sc1 nt
	s_nop 1
	s_mov_b64 s[4:5], 0x90000
	v_lshl_add_u64 v[142:143], v[132:133], 0, s[4:5]
	v_lshl_add_u64 v[144:145], v[136:137], 0, s[4:5]
	global_load_dwordx4 v[184:187], v[142:143], off nt
	global_load_dwordx4 v[188:191], v[144:145], off nt
	global_load_dwordx4 v[192:195], v[142:143], off offset:512 nt
	global_load_dwordx4 v[196:199], v[144:145], off offset:512 nt
	v_mov_b32_dpp v200, v86 quad_perm:[1,0,3,2] row_mask:0xf bank_mask:0xf
	v_cndmask_b32_dpp v201, v82, v200, vcc quad_perm:[1,0,3,2] row_mask:0xf bank_mask:0xf
	v_cndmask_b32_e32 v86, v201, v86, vcc
	v_cndmask_b32_e32 v82, v82, v201, vcc
	v_mov_b32_dpp v200, v87 quad_perm:[1,0,3,2] row_mask:0xf bank_mask:0xf
	v_cndmask_b32_dpp v201, v83, v200, vcc quad_perm:[1,0,3,2] row_mask:0xf bank_mask:0xf
	v_cndmask_b32_e32 v87, v201, v87, vcc
	v_cndmask_b32_e32 v83, v83, v201, vcc
	v_mov_b32_dpp v200, v88 quad_perm:[1,0,3,2] row_mask:0xf bank_mask:0xf
	v_cndmask_b32_dpp v201, v84, v200, vcc quad_perm:[1,0,3,2] row_mask:0xf bank_mask:0xf
	v_cndmask_b32_e32 v88, v201, v88, vcc
	v_cndmask_b32_e32 v84, v84, v201, vcc
	v_mov_b32_dpp v200, v89 quad_perm:[1,0,3,2] row_mask:0xf bank_mask:0xf
	v_cndmask_b32_dpp v201, v85, v200, vcc quad_perm:[1,0,3,2] row_mask:0xf bank_mask:0xf
	v_cndmask_b32_e32 v89, v201, v89, vcc
	v_cndmask_b32_e32 v85, v85, v201, vcc
	v_mov_b32_dpp v200, v94 quad_perm:[1,0,3,2] row_mask:0xf bank_mask:0xf
	v_cndmask_b32_dpp v201, v90, v200, vcc quad_perm:[1,0,3,2] row_mask:0xf bank_mask:0xf
	v_cndmask_b32_e32 v94, v201, v94, vcc
	v_cndmask_b32_e32 v90, v90, v201, vcc
	v_mov_b32_dpp v200, v95 quad_perm:[1,0,3,2] row_mask:0xf bank_mask:0xf
	v_cndmask_b32_dpp v201, v91, v200, vcc quad_perm:[1,0,3,2] row_mask:0xf bank_mask:0xf
	v_cndmask_b32_e32 v95, v201, v95, vcc
	v_cndmask_b32_e32 v91, v91, v201, vcc
	v_mov_b32_dpp v200, v96 quad_perm:[1,0,3,2] row_mask:0xf bank_mask:0xf
	v_cndmask_b32_dpp v201, v92, v200, vcc quad_perm:[1,0,3,2] row_mask:0xf bank_mask:0xf
	v_cndmask_b32_e32 v96, v201, v96, vcc
	v_cndmask_b32_e32 v92, v92, v201, vcc
	v_mov_b32_dpp v200, v97 quad_perm:[1,0,3,2] row_mask:0xf bank_mask:0xf
	v_cndmask_b32_dpp v201, v93, v200, vcc quad_perm:[1,0,3,2] row_mask:0xf bank_mask:0xf
	v_cndmask_b32_e32 v97, v201, v97, vcc
	v_cndmask_b32_e32 v93, v93, v201, vcc
	s_waitcnt vmcnt(20)
;     ...
; #pragma unroll
;     for (int ai = 0; ai < 2; ++ai)
; #pragma unroll
;       for (int m = 0; m < 4; ++m)
;         epi(brow + ai * HALF + wr * 64 + m * 16 + fr, bcol + wc * 32, fq, acc[ai][0][m][0], acc[ai][0][m][1], acc[ai][1][m][0], acc[ai][1][m][1]);
	v_pk_add_f32 v[220:221], v[86:87], v[220:221]
	v_pk_add_f32 v[222:223], v[88:89], v[222:223]
	v_pk_add_f32 v[224:225], v[82:83], v[224:225]
	v_pk_add_f32 v[226:227], v[84:85], v[226:227]
	v_pk_add_f32 v[228:229], v[94:95], v[228:229]
	v_pk_add_f32 v[230:231], v[96:97], v[230:231]
	v_pk_add_f32 v[232:233], v[90:91], v[232:233]
	v_pk_add_f32 v[234:235], v[92:93], v[234:235]
	global_store_dwordx4 v[146:147], v[220:223], off sc1 nt
	global_store_dwordx4 v[148:149], v[224:227], off sc1 nt
	global_store_dwordx4 v[146:147], v[228:231], off offset:512 sc1 nt
	global_store_dwordx4 v[148:149], v[232:235], off offset:512 sc1 nt
	s_nop 1
	s_mov_b64 s[4:5], 0xa0000
	v_lshl_add_u64 v[146:147], v[132:133], 0, s[4:5]
	v_lshl_add_u64 v[148:149], v[136:137], 0, s[4:5]
	global_load_dwordx4 v[220:223], v[146:147], off nt
	global_load_dwordx4 v[224:227], v[148:149], off nt
	global_load_dwordx4 v[228:231], v[146:147], off offset:512 nt
	global_load_dwordx4 v[232:235], v[148:149], off offset:512 nt
	v_mov_b32_dpp v200, v70 quad_perm:[1,0,3,2] row_mask:0xf bank_mask:0xf
	v_cndmask_b32_dpp v201, v66, v200, vcc quad_perm:[1,0,3,2] row_mask:0xf bank_mask:0xf
	v_cndmask_b32_e32 v70, v201, v70, vcc
	v_cndmask_b32_e32 v66, v66, v201, vcc
	v_mov_b32_dpp v200, v71 quad_perm:[1,0,3,2] row_mask:0xf bank_mask:0xf
	v_cndmask_b32_dpp v201, v67, v200, vcc quad_perm:[1,0,3,2] row_mask:0xf bank_mask:0xf
	v_cndmask_b32_e32 v71, v201, v71, vcc
	v_cndmask_b32_e32 v67, v67, v201, vcc
	v_mov_b32_dpp v200, v72 quad_perm:[1,0,3,2] row_mask:0xf bank_mask:0xf
	v_cndmask_b32_dpp v201, v68, v200, vcc quad_perm:[1,0,3,2] row_mask:0xf bank_mask:0xf
	v_cndmask_b32_e32 v72, v201, v72, vcc
	v_cndmask_b32_e32 v68, v68, v201, vcc
	v_mov_b32_dpp v200, v73 quad_perm:[1,0,3,2] row_mask:0xf bank_mask:0xf
	v_cndmask_b32_dpp v201, v69, v200, vcc quad_perm:[1,0,3,2] row_mask:0xf bank_mask:0xf
	v_cndmask_b32_e32 v73, v201, v73, vcc
	v_cndmask_b32_e32 v69, v69, v201, vcc
	v_mov_b32_dpp v200, v78 quad_perm:[1,0,3,2] row_mask:0xf bank_mask:0xf
	v_cndmask_b32_dpp v201, v74, v200, vcc quad_perm:[1,0,3,2] row_mask:0xf bank_mask:0xf
	v_cndmask_b32_e32 v78, v201, v78, vcc
	v_cndmask_b32_e32 v74, v74, v201, vcc
	v_mov_b32_dpp v200, v79 quad_perm:[1,0,3,2] row_mask:0xf bank_mask:0xf
	v_cndmask_b32_dpp v201, v75, v200, vcc quad_perm:[1,0,3,2] row_mask:0xf bank_mask:0xf
	v_cndmask_b32_e32 v79, v201, v79, vcc
	v_cndmask_b32_e32 v75, v75, v201, vcc
	v_mov_b32_dpp v200, v80 quad_perm:[1,0,3,2] row_mask:0xf bank_mask:0xf
	v_cndmask_b32_dpp v201, v76, v200, vcc quad_perm:[1,0,3,2] row_mask:0xf bank_mask:0xf
	v_cndmask_b32_e32 v80, v201, v80, vcc
	v_cndmask_b32_e32 v76, v76, v201, vcc
	v_mov_b32_dpp v200, v81 quad_perm:[1,0,3,2] row_mask:0xf bank_mask:0xf
	v_cndmask_b32_dpp v201, v77, v200, vcc quad_perm:[1,0,3,2] row_mask:0xf bank_mask:0xf
	v_cndmask_b32_e32 v81, v201, v81, vcc
	v_cndmask_b32_e32 v77, v77, v201, vcc
	s_waitcnt vmcnt(24)
	v_pk_add_f32 v[236:237], v[70:71], v[236:237]
	v_pk_add_f32 v[238:239], v[72:73], v[238:239]
	v_pk_add_f32 v[240:241], v[66:67], v[240:241]
	v_pk_add_f32 v[242:243], v[68:69], v[242:243]
	v_pk_add_f32 v[244:245], v[78:79], v[244:245]
	v_pk_add_f32 v[246:247], v[80:81], v[246:247]
	v_pk_add_f32 v[248:249], v[74:75], v[248:249]
	v_pk_add_f32 v[250:251], v[76:77], v[250:251]
	global_store_dwordx4 v[150:151], v[236:239], off sc1 nt
	global_store_dwordx4 v[152:153], v[240:243], off sc1 nt
	global_store_dwordx4 v[150:151], v[244:247], off offset:512 sc1 nt
	global_store_dwordx4 v[152:153], v[248:251], off offset:512 sc1 nt
	s_nop 1
	s_mov_b64 s[4:5], 0xb0000
	v_lshl_add_u64 v[150:151], v[132:133], 0, s[4:5]
	v_lshl_add_u64 v[152:153], v[136:137], 0, s[4:5]
	global_load_dwordx4 v[236:239], v[150:151], off nt
	global_load_dwordx4 v[240:243], v[152:153], off nt
	global_load_dwordx4 v[244:247], v[150:151], off offset:512 nt
	global_load_dwordx4 v[248:251], v[152:153], off offset:512 nt
	v_mov_b32_dpp v200, v54 quad_perm:[1,0,3,2] row_mask:0xf bank_mask:0xf
	v_cndmask_b32_dpp v201, v50, v200, vcc quad_perm:[1,0,3,2] row_mask:0xf bank_mask:0xf
	v_cndmask_b32_e32 v54, v201, v54, vcc
	v_cndmask_b32_e32 v50, v50, v201, vcc
	v_mov_b32_dpp v200, v55 quad_perm:[1,0,3,2] row_mask:0xf bank_mask:0xf
	v_cndmask_b32_dpp v201, v51, v200, vcc quad_perm:[1,0,3,2] row_mask:0xf bank_mask:0xf
	v_cndmask_b32_e32 v55, v201, v55, vcc
	v_cndmask_b32_e32 v51, v51, v201, vcc
	v_mov_b32_dpp v200, v56 quad_perm:[1,0,3,2] row_mask:0xf bank_mask:0xf
	v_cndmask_b32_dpp v201, v52, v200, vcc quad_perm:[1,0,3,2] row_mask:0xf bank_mask:0xf
	v_cndmask_b32_e32 v56, v201, v56, vcc
	v_cndmask_b32_e32 v52, v52, v201, vcc
	v_mov_b32_dpp v200, v57 quad_perm:[1,0,3,2] row_mask:0xf bank_mask:0xf
	v_cndmask_b32_dpp v201, v53, v200, vcc quad_perm:[1,0,3,2] row_mask:0xf bank_mask:0xf
	v_cndmask_b32_e32 v57, v201, v57, vcc
	v_cndmask_b32_e32 v53, v53, v201, vcc
	v_mov_b32_dpp v200, v62 quad_perm:[1,0,3,2] row_mask:0xf bank_mask:0xf
	v_cndmask_b32_dpp v201, v58, v200, vcc quad_perm:[1,0,3,2] row_mask:0xf bank_mask:0xf
	v_cndmask_b32_e32 v62, v201, v62, vcc
	v_cndmask_b32_e32 v58, v58, v201, vcc
	v_mov_b32_dpp v200, v63 quad_perm:[1,0,3,2] row_mask:0xf bank_mask:0xf
	v_cndmask_b32_dpp v201, v59, v200, vcc quad_perm:[1,0,3,2] row_mask:0xf bank_mask:0xf
	v_cndmask_b32_e32 v63, v201, v63, vcc
	v_cndmask_b32_e32 v59, v59, v201, vcc
	v_mov_b32_dpp v200, v64 quad_perm:[1,0,3,2] row_mask:0xf bank_mask:0xf
	v_cndmask_b32_dpp v201, v60, v200, vcc quad_perm:[1,0,3,2] row_mask:0xf bank_mask:0xf
	v_cndmask_b32_e32 v64, v201, v64, vcc
	v_cndmask_b32_e32 v60, v60, v201, vcc
	v_mov_b32_dpp v200, v65 quad_perm:[1,0,3,2] row_mask:0xf bank_mask:0xf
	v_cndmask_b32_dpp v201, v61, v200, vcc quad_perm:[1,0,3,2] row_mask:0xf bank_mask:0xf
	v_cndmask_b32_e32 v65, v201, v65, vcc
	v_cndmask_b32_e32 v61, v61, v201, vcc
	s_waitcnt vmcnt(24)
;     ...
; #pragma unroll
;     for (int ai = 0; ai < 2; ++ai)
; #pragma unroll
;       for (int m = 0; m < 4; ++m)
;         epi(brow + ai * HALF + wr * 64 + m * 16 + fr, bcol + wc * 32, fq, acc[ai][0][m][0], acc[ai][0][m][1], acc[ai][1][m][0], acc[ai][1][m][1]);
	v_pk_add_f32 v[168:169], v[54:55], v[168:169]
	v_pk_add_f32 v[170:171], v[56:57], v[170:171]
	v_pk_add_f32 v[172:173], v[50:51], v[172:173]
	v_pk_add_f32 v[174:175], v[52:53], v[174:175]
	v_pk_add_f32 v[176:177], v[62:63], v[176:177]
	v_pk_add_f32 v[178:179], v[64:65], v[178:179]
	v_pk_add_f32 v[180:181], v[58:59], v[180:181]
	v_pk_add_f32 v[182:183], v[60:61], v[182:183]
	global_store_dwordx4 v[138:139], v[168:171], off sc1 nt
	global_store_dwordx4 v[140:141], v[172:175], off sc1 nt
	global_store_dwordx4 v[138:139], v[176:179], off offset:512 sc1 nt
	global_store_dwordx4 v[140:141], v[180:183], off offset:512 sc1 nt
	v_mov_b32_dpp v200, v38 quad_perm:[1,0,3,2] row_mask:0xf bank_mask:0xf
	v_cndmask_b32_dpp v201, v34, v200, vcc quad_perm:[1,0,3,2] row_mask:0xf bank_mask:0xf
	v_cndmask_b32_e32 v38, v201, v38, vcc
	v_cndmask_b32_e32 v34, v34, v201, vcc
	v_mov_b32_dpp v200, v39 quad_perm:[1,0,3,2] row_mask:0xf bank_mask:0xf
	v_cndmask_b32_dpp v201, v35, v200, vcc quad_perm:[1,0,3,2] row_mask:0xf bank_mask:0xf
	v_cndmask_b32_e32 v39, v201, v39, vcc
	v_cndmask_b32_e32 v35, v35, v201, vcc
	v_mov_b32_dpp v200, v40 quad_perm:[1,0,3,2] row_mask:0xf bank_mask:0xf
	v_cndmask_b32_dpp v201, v36, v200, vcc quad_perm:[1,0,3,2] row_mask:0xf bank_mask:0xf
	v_cndmask_b32_e32 v40, v201, v40, vcc
	v_cndmask_b32_e32 v36, v36, v201, vcc
	v_mov_b32_dpp v200, v41 quad_perm:[1,0,3,2] row_mask:0xf bank_mask:0xf
	v_cndmask_b32_dpp v201, v37, v200, vcc quad_perm:[1,0,3,2] row_mask:0xf bank_mask:0xf
	v_cndmask_b32_e32 v41, v201, v41, vcc
	v_cndmask_b32_e32 v37, v37, v201, vcc
	v_mov_b32_dpp v200, v46 quad_perm:[1,0,3,2] row_mask:0xf bank_mask:0xf
	v_cndmask_b32_dpp v201, v42, v200, vcc quad_perm:[1,0,3,2] row_mask:0xf bank_mask:0xf
	v_cndmask_b32_e32 v46, v201, v46, vcc
	v_cndmask_b32_e32 v42, v42, v201, vcc
	v_mov_b32_dpp v200, v47 quad_perm:[1,0,3,2] row_mask:0xf bank_mask:0xf
	v_cndmask_b32_dpp v201, v43, v200, vcc quad_perm:[1,0,3,2] row_mask:0xf bank_mask:0xf
	v_cndmask_b32_e32 v47, v201, v47, vcc
	v_cndmask_b32_e32 v43, v43, v201, vcc
	v_mov_b32_dpp v200, v48 quad_perm:[1,0,3,2] row_mask:0xf bank_mask:0xf
	v_cndmask_b32_dpp v201, v44, v200, vcc quad_perm:[1,0,3,2] row_mask:0xf bank_mask:0xf
	v_cndmask_b32_e32 v48, v201, v48, vcc
	v_cndmask_b32_e32 v44, v44, v201, vcc
	v_mov_b32_dpp v200, v49 quad_perm:[1,0,3,2] row_mask:0xf bank_mask:0xf
	v_cndmask_b32_dpp v201, v45, v200, vcc quad_perm:[1,0,3,2] row_mask:0xf bank_mask:0xf
	v_cndmask_b32_e32 v49, v201, v49, vcc
	v_cndmask_b32_e32 v45, v45, v201, vcc
	s_waitcnt vmcnt(20)
	v_pk_add_f32 v[184:185], v[38:39], v[184:185]
	v_pk_add_f32 v[186:187], v[40:41], v[186:187]
	v_pk_add_f32 v[188:189], v[34:35], v[188:189]
	v_pk_add_f32 v[190:191], v[36:37], v[190:191]
	v_pk_add_f32 v[192:193], v[46:47], v[192:193]
	v_pk_add_f32 v[194:195], v[48:49], v[194:195]
	v_pk_add_f32 v[196:197], v[42:43], v[196:197]
	v_pk_add_f32 v[198:199], v[44:45], v[198:199]
	global_store_dwordx4 v[142:143], v[184:187], off sc1 nt
	global_store_dwordx4 v[144:145], v[188:191], off sc1 nt
	global_store_dwordx4 v[142:143], v[192:195], off offset:512 sc1 nt
	global_store_dwordx4 v[144:145], v[196:199], off offset:512 sc1 nt
	v_mov_b32_dpp v200, v22 quad_perm:[1,0,3,2] row_mask:0xf bank_mask:0xf
	v_cndmask_b32_dpp v201, v18, v200, vcc quad_perm:[1,0,3,2] row_mask:0xf bank_mask:0xf
	v_cndmask_b32_e32 v22, v201, v22, vcc
	v_cndmask_b32_e32 v18, v18, v201, vcc
	v_mov_b32_dpp v200, v23 quad_perm:[1,0,3,2] row_mask:0xf bank_mask:0xf
	v_cndmask_b32_dpp v201, v19, v200, vcc quad_perm:[1,0,3,2] row_mask:0xf bank_mask:0xf
	v_cndmask_b32_e32 v23, v201, v23, vcc
	v_cndmask_b32_e32 v19, v19, v201, vcc
	v_mov_b32_dpp v200, v24 quad_perm:[1,0,3,2] row_mask:0xf bank_mask:0xf
	v_cndmask_b32_dpp v201, v20, v200, vcc quad_perm:[1,0,3,2] row_mask:0xf bank_mask:0xf
	v_cndmask_b32_e32 v24, v201, v24, vcc
	v_cndmask_b32_e32 v20, v20, v201, vcc
	v_mov_b32_dpp v200, v25 quad_perm:[1,0,3,2] row_mask:0xf bank_mask:0xf
	v_cndmask_b32_dpp v201, v21, v200, vcc quad_perm:[1,0,3,2] row_mask:0xf bank_mask:0xf
	v_cndmask_b32_e32 v25, v201, v25, vcc
	v_cndmask_b32_e32 v21, v21, v201, vcc
	v_mov_b32_dpp v200, v30 quad_perm:[1,0,3,2] row_mask:0xf bank_mask:0xf
	v_cndmask_b32_dpp v201, v26, v200, vcc quad_perm:[1,0,3,2] row_mask:0xf bank_mask:0xf
	v_cndmask_b32_e32 v30, v201, v30, vcc
	v_cndmask_b32_e32 v26, v26, v201, vcc
	v_mov_b32_dpp v200, v31 quad_perm:[1,0,3,2] row_mask:0xf bank_mask:0xf
	v_cndmask_b32_dpp v201, v27, v200, vcc quad_perm:[1,0,3,2] row_mask:0xf bank_mask:0xf
	v_cndmask_b32_e32 v31, v201, v31, vcc
	v_cndmask_b32_e32 v27, v27, v201, vcc
	v_mov_b32_dpp v200, v32 quad_perm:[1,0,3,2] row_mask:0xf bank_mask:0xf
	v_cndmask_b32_dpp v201, v28, v200, vcc quad_perm:[1,0,3,2] row_mask:0xf bank_mask:0xf
	v_cndmask_b32_e32 v32, v201, v32, vcc
	v_cndmask_b32_e32 v28, v28, v201, vcc
	v_mov_b32_dpp v200, v33 quad_perm:[1,0,3,2] row_mask:0xf bank_mask:0xf
	v_cndmask_b32_dpp v201, v29, v200, vcc quad_perm:[1,0,3,2] row_mask:0xf bank_mask:0xf
	v_cndmask_b32_e32 v33, v201, v33, vcc
	v_cndmask_b32_e32 v29, v29, v201, vcc
	s_waitcnt vmcnt(16)
; #define WAIT_V(n) asm volatile("s_waitcnt vmcnt(" #n ")" ::: "memory")
;     ...
; #pragma unroll
;     for (int ai = 0; ai < 2; ++ai)
; #pragma unroll
;       for (int m = 0; m < 4; ++m)
;         epi(brow + ai * HALF + wr * 64 + m * 16 + fr, bcol + wc * 32, fq, acc[ai][0][m][0], acc[ai][0][m][1], acc[ai][1][m][0], acc[ai][1][m][1]);
;   }
;   if (!have_next) { WAIT_V(0); __syncthreads(); }
	v_pk_add_f32 v[220:221], v[22:23], v[220:221]
	v_pk_add_f32 v[222:223], v[24:25], v[222:223]
	v_pk_add_f32 v[224:225], v[18:19], v[224:225]
	v_pk_add_f32 v[226:227], v[20:21], v[226:227]
	v_pk_add_f32 v[228:229], v[30:31], v[228:229]
	v_pk_add_f32 v[230:231], v[32:33], v[230:231]
	v_pk_add_f32 v[232:233], v[26:27], v[232:233]
	v_pk_add_f32 v[234:235], v[28:29], v[234:235]
	global_store_dwordx4 v[146:147], v[220:223], off sc1 nt
	global_store_dwordx4 v[148:149], v[224:227], off sc1 nt
	global_store_dwordx4 v[146:147], v[228:231], off offset:512 sc1 nt
	global_store_dwordx4 v[148:149], v[232:235], off offset:512 sc1 nt
	v_mov_b32_dpp v200, v14 quad_perm:[1,0,3,2] row_mask:0xf bank_mask:0xf
	v_cndmask_b32_dpp v201, v6, v200, vcc quad_perm:[1,0,3,2] row_mask:0xf bank_mask:0xf
	v_cndmask_b32_e32 v14, v201, v14, vcc
	v_cndmask_b32_e32 v6, v6, v201, vcc
	v_mov_b32_dpp v200, v15 quad_perm:[1,0,3,2] row_mask:0xf bank_mask:0xf
	v_cndmask_b32_dpp v201, v7, v200, vcc quad_perm:[1,0,3,2] row_mask:0xf bank_mask:0xf
	v_cndmask_b32_e32 v15, v201, v15, vcc
	v_cndmask_b32_e32 v7, v7, v201, vcc
	v_mov_b32_dpp v200, v16 quad_perm:[1,0,3,2] row_mask:0xf bank_mask:0xf
	v_cndmask_b32_dpp v201, v8, v200, vcc quad_perm:[1,0,3,2] row_mask:0xf bank_mask:0xf
	v_cndmask_b32_e32 v16, v201, v16, vcc
	v_cndmask_b32_e32 v8, v8, v201, vcc
	v_mov_b32_dpp v200, v17 quad_perm:[1,0,3,2] row_mask:0xf bank_mask:0xf
	v_cndmask_b32_dpp v201, v9, v200, vcc quad_perm:[1,0,3,2] row_mask:0xf bank_mask:0xf
	v_cndmask_b32_e32 v17, v201, v17, vcc
	v_cndmask_b32_e32 v9, v9, v201, vcc
	v_mov_b32_dpp v200, v10 quad_perm:[1,0,3,2] row_mask:0xf bank_mask:0xf
	v_cndmask_b32_dpp v201, v2, v200, vcc quad_perm:[1,0,3,2] row_mask:0xf bank_mask:0xf
	v_cndmask_b32_e32 v10, v201, v10, vcc
	v_cndmask_b32_e32 v2, v2, v201, vcc
	v_mov_b32_dpp v200, v11 quad_perm:[1,0,3,2] row_mask:0xf bank_mask:0xf
	v_cndmask_b32_dpp v201, v3, v200, vcc quad_perm:[1,0,3,2] row_mask:0xf bank_mask:0xf
	v_cndmask_b32_e32 v11, v201, v11, vcc
	v_cndmask_b32_e32 v3, v3, v201, vcc
	v_mov_b32_dpp v200, v12 quad_perm:[1,0,3,2] row_mask:0xf bank_mask:0xf
	v_cndmask_b32_dpp v201, v4, v200, vcc quad_perm:[1,0,3,2] row_mask:0xf bank_mask:0xf
	v_cndmask_b32_e32 v12, v201, v12, vcc
	v_cndmask_b32_e32 v4, v4, v201, vcc
	v_mov_b32_dpp v200, v13 quad_perm:[1,0,3,2] row_mask:0xf bank_mask:0xf
	v_cndmask_b32_dpp v201, v5, v200, vcc quad_perm:[1,0,3,2] row_mask:0xf bank_mask:0xf
	v_cndmask_b32_e32 v13, v201, v13, vcc
	v_cndmask_b32_e32 v5, v5, v201, vcc
	s_waitcnt vmcnt(12)
	v_pk_add_f32 v[236:237], v[14:15], v[236:237]
	v_pk_add_f32 v[238:239], v[16:17], v[238:239]
	v_pk_add_f32 v[240:241], v[6:7], v[240:241]
	v_pk_add_f32 v[242:243], v[8:9], v[242:243]
	v_pk_add_f32 v[244:245], v[10:11], v[244:245]
	v_pk_add_f32 v[246:247], v[12:13], v[246:247]
	v_pk_add_f32 v[248:249], v[2:3], v[248:249]
	v_pk_add_f32 v[250:251], v[4:5], v[250:251]
	global_store_dwordx4 v[150:151], v[236:239], off sc1 nt
	global_store_dwordx4 v[152:153], v[240:243], off sc1 nt
	global_store_dwordx4 v[150:151], v[244:247], off offset:512 sc1 nt
	global_store_dwordx4 v[152:153], v[248:251], off offset:512 sc1 nt
	v_cmp_ne_u32_e64 s[4:5], 1, v0
	s_andn2_b64 vcc, exec, s[2:3]
	s_cbranch_vccnz .LBB0_1551
	s_waitcnt vmcnt(0)
	s_waitcnt lgkmcnt(0)
	s_barrier
	s_branch .LBB0_1551
